# B1 forward substitution: LDS broadcast reads pipelined 10 deep into pool regs v76-155
# speedup vs baseline: 1.1931x; 1.0084x over previous
; DI void phaseB1(const Params& p, int l, char* smem) {
;     ...
; #pragma unroll
;       for (int i = 1; i < 64; ++i) {
;         float s0 = 0.f, s1 = 0.f, s2 = 0.f, s3 = 0.f;
; #pragma unroll
;         for (int j4 = 0; j4 < i; j4 += 4) {
;           const float4 a = *(const float4*)(Am + i * 68 + j4);
;           s0 += a.x * x[j4];
;           if (j4 + 1 < i) s1 += a.y * x[j4 + 1];
;           if (j4 + 2 < i) s2 += a.z * x[j4 + 2];
;           if (j4 + 3 < i) s3 += a.w * x[j4 + 3];
;         }
;         x[i] = x[i] - ((s0 + s1) + (s2 + s3));
;       }
.LBB0_1949:
	s_or_b64 exec, exec, s[88:89]
	ds_read_b32 v76, v1 offset:272
	ds_read_b64 v[80:81], v1 offset:544
	ds_read_b96 v[84:86], v1 offset:816
	ds_read_b32 v88, v1 offset:1376
	ds_read_b128 v[92:95], v1 offset:1088
	ds_read_b128 v[96:99], v1 offset:1360
	ds_read_b128 v[100:103], v1 offset:1632
	ds_read_b64 v[104:105], v1 offset:1648
	ds_read_b128 v[108:111], v1 offset:1904
	ds_read_b96 v[112:114], v1 offset:1920
	ds_read_b128 v[116:119], v1 offset:2176
	ds_read_b128 v[120:123], v1 offset:2192
	ds_read_b128 v[124:127], v1 offset:2448
	s_waitcnt lgkmcnt(12)
	v_fma_f32 v0, v58, v76, 0
	v_sub_f32_e32 v0, v59, v0
	s_waitcnt lgkmcnt(11)
	v_fma_f32 v4, v58, v80, 0
	v_fma_f32 v5, v81, v0, 0
	v_add_f32_e32 v4, v4, v5
	v_sub_f32_e32 v4, v72, v4
	s_waitcnt lgkmcnt(10)
	v_fma_f32 v5, v58, v84, 0
	v_fma_f32 v59, v0, v85, 0
	v_fma_f32 v60, v86, v4, 0
	v_add_f32_e32 v5, v5, v59
	v_add_f32_e32 v5, v5, v60
	ds_read_b128 v[76:79], v1 offset:2464
	ds_read_b32 v80, v1 offset:2480
	v_sub_f32_e32 v5, v73, v5
	s_waitcnt lgkmcnt(10)
	v_fma_f32 v59, v58, v92, 0
	v_fma_f32 v60, v0, v93, 0
	v_fma_f32 v61, v94, v4, 0
	v_fma_f32 v62, v95, v5, 0
	v_add_f32_e32 v59, v59, v60
	v_add_f32_e32 v60, v61, v62
	v_add_f32_e32 v59, v59, v60
	ds_read_b128 v[84:87], v1 offset:2720
	v_sub_f32_e32 v59, v70, v59
	s_waitcnt lgkmcnt(10)
	v_fma_f32 v60, v58, v96, 0
	v_fma_f32 v61, v0, v97, 0
	v_fma_f32 v62, v4, v98, 0
	v_fma_f32 v63, v5, v99, 0
	v_fmac_f32_e32 v60, v88, v59
	v_add_f32_e32 v60, v61, v60
	v_add_f32_e32 v61, v62, v63
	ds_read_b128 v[88:91], v1 offset:2736
	v_add_f32_e32 v60, v61, v60
	v_sub_f32_e32 v60, v71, v60
	s_waitcnt lgkmcnt(10)
	v_fma_f32 v61, v58, v100, 0
	v_fma_f32 v70, v0, v101, 0
	ds_read_b64 v[92:93], v1 offset:2752
	v_fma_f32 v64, v4, v102, 0
	v_fma_f32 v65, v5, v103, 0
	s_waitcnt lgkmcnt(10)
	v_fmac_f32_e32 v61, v59, v104
	v_fmac_f32_e32 v70, v105, v60
	v_add_f32_e32 v61, v61, v70
	v_add_f32_e32 v62, v64, v65
	v_add_f32_e32 v61, v62, v61
	ds_read_b128 v[96:99], v1 offset:2992
	v_sub_f32_e32 v61, v68, v61
	s_waitcnt lgkmcnt(10)
	v_fma_f32 v68, v58, v108, 0
	v_fma_f32 v70, v0, v109, 0
	v_fma_f32 v71, v4, v110, 0
	ds_read_b128 v[100:103], v1 offset:3008
	v_fma_f32 v65, v5, v111, 0
	s_waitcnt lgkmcnt(10)
	v_fmac_f32_e32 v68, v59, v112
	v_fmac_f32_e32 v70, v60, v113
	v_fmac_f32_e32 v71, v114, v61
	v_add_f32_e32 v62, v68, v70
	v_add_f32_e32 v63, v65, v71
	v_add_f32_e32 v62, v63, v62
	v_sub_f32_e32 v62, v69, v62
	ds_read_b96 v[104:106], v1 offset:3024
	s_waitcnt lgkmcnt(10)
	v_fma_f32 v63, v58, v116, 0
	v_fma_f32 v64, v0, v117, 0
	v_fma_f32 v65, v4, v118, 0
	v_fma_f32 v72, v5, v119, 0
	ds_read_b128 v[108:111], v1 offset:3264
	s_waitcnt lgkmcnt(10)
	v_fmac_f32_e32 v63, v59, v120
	v_fmac_f32_e32 v64, v60, v121
	v_fmac_f32_e32 v65, v61, v122
	v_fmac_f32_e32 v72, v62, v123
	ds_read_b128 v[112:115], v1 offset:3280
	v_add_f32_e32 v63, v63, v64
	v_add_f32_e32 v64, v65, v72
	v_add_f32_e32 v63, v64, v63
	v_sub_f32_e32 v63, v66, v63
	s_waitcnt lgkmcnt(10)
	v_fma_f32 v64, v58, v124, 0
	v_fma_f32 v65, v0, v125, 0
	v_fma_f32 v66, v4, v126, 0
	v_fma_f32 v72, v5, v127, 0
	ds_read_b128 v[116:119], v1 offset:3296
	s_waitcnt lgkmcnt(10)
	v_fmac_f32_e32 v64, v59, v76
	ds_read_b128 v[120:123], v1 offset:3536
	v_fmac_f32_e32 v65, v60, v77
	v_fmac_f32_e32 v66, v61, v78
	v_fmac_f32_e32 v72, v62, v79
	s_waitcnt lgkmcnt(10)
	v_fmac_f32_e32 v64, v63, v80
	v_add_f32_e32 v64, v65, v64
	v_add_f32_e32 v65, v66, v72
	v_add_f32_e32 v64, v65, v64
	v_sub_f32_e32 v64, v67, v64
	ds_read_b128 v[76:79], v1 offset:3552
	s_waitcnt lgkmcnt(10)
	v_fma_f32 v65, v58, v84, 0
	v_fma_f32 v70, v0, v85, 0
	v_fma_f32 v71, v4, v86, 0
	v_fma_f32 v72, v5, v87, 0
	ds_read_b128 v[80:83], v1 offset:3568
	s_waitcnt lgkmcnt(10)
	v_fmac_f32_e32 v65, v59, v88
	v_fmac_f32_e32 v70, v60, v89
	ds_read_b32 v84, v1 offset:3584
	v_fmac_f32_e32 v71, v61, v90
	v_fmac_f32_e32 v72, v62, v91
	s_waitcnt lgkmcnt(10)
	v_fmac_f32_e32 v65, v63, v92
	v_fmac_f32_e32 v70, v64, v93
	v_add_f32_e32 v65, v65, v70
	v_add_f32_e32 v66, v71, v72
	v_add_f32_e32 v65, v66, v65
	ds_read_b128 v[88:91], v1 offset:3808
	v_sub_f32_e32 v56, v56, v65
	s_waitcnt lgkmcnt(10)
	v_fma_f32 v65, v58, v96, 0
	v_fma_f32 v70, v0, v97, 0
	v_fma_f32 v71, v4, v98, 0
	v_fma_f32 v72, v5, v99, 0
	ds_read_b128 v[92:95], v1 offset:3824
	s_waitcnt lgkmcnt(10)
	v_fmac_f32_e32 v65, v59, v100
	v_fmac_f32_e32 v70, v60, v101
	v_fmac_f32_e32 v71, v61, v102
	ds_read_b128 v[96:99], v1 offset:3840
	v_fmac_f32_e32 v72, v62, v103
	s_waitcnt lgkmcnt(10)
	v_fmac_f32_e32 v65, v63, v104
	v_fmac_f32_e32 v70, v64, v105
	v_fmac_f32_e32 v71, v56, v106
	v_add_f32_e32 v65, v65, v70
	v_add_f32_e32 v66, v72, v71
	v_add_f32_e32 v65, v66, v65
	ds_read_b64 v[100:101], v1 offset:3856
	v_sub_f32_e32 v57, v57, v65
	s_waitcnt lgkmcnt(10)
	v_fma_f32 v65, v58, v108, 0
	v_fma_f32 v70, v0, v109, 0
	v_fma_f32 v71, v4, v110, 0
	v_fma_f32 v72, v5, v111, 0
	ds_read_b128 v[104:107], v1 offset:4080
	s_waitcnt lgkmcnt(10)
	v_fmac_f32_e32 v65, v59, v112
	v_fmac_f32_e32 v70, v60, v113
	v_fmac_f32_e32 v71, v61, v114
	v_fmac_f32_e32 v72, v62, v115
	ds_read_b128 v[108:111], v1 offset:4096
	s_waitcnt lgkmcnt(10)
	v_fmac_f32_e32 v65, v63, v116
	v_fmac_f32_e32 v70, v64, v117
	v_fmac_f32_e32 v71, v56, v118
	v_fmac_f32_e32 v72, v57, v119
	v_add_f32_e32 v65, v65, v70
	v_add_f32_e32 v66, v71, v72
	v_add_f32_e32 v65, v66, v65
	ds_read_b128 v[112:115], v1 offset:4112
	v_sub_f32_e32 v54, v54, v65
	s_waitcnt lgkmcnt(10)
	v_fma_f32 v65, v58, v120, 0
	v_fma_f32 v70, v0, v121, 0
	v_fma_f32 v71, v4, v122, 0
	v_fma_f32 v72, v5, v123, 0
	ds_read_b96 v[116:118], v1 offset:4128
	s_waitcnt lgkmcnt(10)
; DI void phaseB1(const Params& p, int l, char* smem) {
;     ...
; #pragma unroll
;       for (int i = 1; i < 64; ++i) {
;         float s0 = 0.f, s1 = 0.f, s2 = 0.f, s3 = 0.f;
; #pragma unroll
;         for (int j4 = 0; j4 < i; j4 += 4) {
;           const float4 a = *(const float4*)(Am + i * 68 + j4);
;           s0 += a.x * x[j4];
;           if (j4 + 1 < i) s1 += a.y * x[j4 + 1];
;           if (j4 + 2 < i) s2 += a.z * x[j4 + 2];
;           if (j4 + 3 < i) s3 += a.w * x[j4 + 3];
;         }
;         x[i] = x[i] - ((s0 + s1) + (s2 + s3));
;       }
	v_fmac_f32_e32 v65, v59, v76
	v_fmac_f32_e32 v70, v60, v77
	v_fmac_f32_e32 v71, v61, v78
	v_fmac_f32_e32 v72, v62, v79
	ds_read_b128 v[76:79], v1 offset:4352
	s_waitcnt lgkmcnt(10)
	v_fmac_f32_e32 v65, v63, v80
	ds_read_b128 v[120:123], v1 offset:4368
	v_fmac_f32_e32 v70, v64, v81
	v_fmac_f32_e32 v71, v56, v82
	v_fmac_f32_e32 v72, v57, v83
	s_waitcnt lgkmcnt(10)
	v_fmac_f32_e32 v65, v54, v84
	v_add_f32_e32 v65, v70, v65
	v_add_f32_e32 v66, v71, v72
	v_add_f32_e32 v65, v66, v65
	ds_read_b128 v[80:83], v1 offset:4384
	v_sub_f32_e32 v55, v55, v65
	s_waitcnt lgkmcnt(10)
	v_fma_f32 v65, v58, v88, 0
	v_fma_f32 v70, v0, v89, 0
	v_fma_f32 v71, v4, v90, 0
	v_fma_f32 v72, v5, v91, 0
	ds_read_b128 v[84:87], v1 offset:4400
	s_waitcnt lgkmcnt(10)
	v_fmac_f32_e32 v65, v59, v92
	v_fmac_f32_e32 v70, v60, v93
	v_fmac_f32_e32 v71, v61, v94
	v_fmac_f32_e32 v72, v62, v95
	ds_read_b128 v[88:91], v1 offset:4624
	s_waitcnt lgkmcnt(10)
	v_fmac_f32_e32 v65, v63, v96
	v_fmac_f32_e32 v70, v64, v97
	ds_read_b128 v[92:95], v1 offset:4640
	v_fmac_f32_e32 v71, v56, v98
	v_fmac_f32_e32 v72, v57, v99
	s_waitcnt lgkmcnt(10)
	v_fmac_f32_e32 v65, v54, v100
	v_fmac_f32_e32 v70, v55, v101
	v_add_f32_e32 v65, v65, v70
	v_add_f32_e32 v66, v71, v72
	v_add_f32_e32 v65, v66, v65
	ds_read_b128 v[96:99], v1 offset:4656
	v_sub_f32_e32 v52, v52, v65
	s_waitcnt lgkmcnt(10)
	v_fma_f32 v65, v58, v104, 0
	v_fma_f32 v70, v0, v105, 0
	v_fma_f32 v71, v4, v106, 0
	v_fma_f32 v72, v5, v107, 0
	ds_read_b128 v[100:103], v1 offset:4672
	s_waitcnt lgkmcnt(10)
	v_fmac_f32_e32 v65, v59, v108
	v_fmac_f32_e32 v70, v60, v109
	v_fmac_f32_e32 v71, v61, v110
	v_fmac_f32_e32 v72, v62, v111
	ds_read_b32 v104, v1 offset:4688
	s_waitcnt lgkmcnt(10)
	v_fmac_f32_e32 v65, v63, v112
	v_fmac_f32_e32 v70, v64, v113
	v_fmac_f32_e32 v71, v56, v114
	ds_read_b128 v[108:111], v1 offset:4896
	v_fmac_f32_e32 v72, v57, v115
	s_waitcnt lgkmcnt(10)
	v_fmac_f32_e32 v65, v54, v116
	v_fmac_f32_e32 v70, v55, v117
	v_fmac_f32_e32 v71, v52, v118
	v_add_f32_e32 v65, v65, v70
	v_add_f32_e32 v66, v72, v71
	v_add_f32_e32 v65, v66, v65
	ds_read_b128 v[112:115], v1 offset:4912
	v_sub_f32_e32 v53, v53, v65
	s_waitcnt lgkmcnt(10)
	v_fma_f32 v65, v58, v76, 0
	v_fma_f32 v70, v0, v77, 0
	v_fma_f32 v71, v4, v78, 0
	v_fma_f32 v72, v5, v79, 0
	ds_read_b128 v[76:79], v1 offset:4928
	s_waitcnt lgkmcnt(10)
	v_fmac_f32_e32 v65, v59, v120
	v_fmac_f32_e32 v70, v60, v121
	v_fmac_f32_e32 v71, v61, v122
	v_fmac_f32_e32 v72, v62, v123
	ds_read_b128 v[116:119], v1 offset:4944
	s_waitcnt lgkmcnt(10)
	v_fmac_f32_e32 v65, v63, v80
	v_fmac_f32_e32 v70, v64, v81
	v_fmac_f32_e32 v71, v56, v82
	v_fmac_f32_e32 v72, v57, v83
	ds_read_b64 v[80:81], v1 offset:4960
	s_waitcnt lgkmcnt(10)
	v_fmac_f32_e32 v65, v54, v84
	v_fmac_f32_e32 v70, v55, v85
	v_fmac_f32_e32 v71, v52, v86
	v_fmac_f32_e32 v72, v53, v87
	v_add_f32_e32 v65, v65, v70
	v_add_f32_e32 v66, v71, v72
	v_add_f32_e32 v65, v66, v65
	ds_read_b128 v[84:87], v1 offset:5168
	v_sub_f32_e32 v50, v50, v65
	s_waitcnt lgkmcnt(10)
	v_fma_f32 v65, v58, v88, 0
	v_fma_f32 v70, v0, v89, 0
	v_fma_f32 v71, v4, v90, 0
	v_fma_f32 v72, v5, v91, 0
	ds_read_b128 v[88:91], v1 offset:5184
	s_waitcnt lgkmcnt(10)
	v_fmac_f32_e32 v65, v59, v92
	v_fmac_f32_e32 v70, v60, v93
	v_fmac_f32_e32 v71, v61, v94
	v_fmac_f32_e32 v72, v62, v95
	ds_read_b128 v[92:95], v1 offset:5200
	s_waitcnt lgkmcnt(10)
	v_fmac_f32_e32 v65, v63, v96
	v_fmac_f32_e32 v70, v64, v97
	v_fmac_f32_e32 v71, v56, v98
	v_fmac_f32_e32 v72, v57, v99
	ds_read_b128 v[96:99], v1 offset:5216
	s_waitcnt lgkmcnt(10)
	v_fmac_f32_e32 v65, v54, v100
	ds_read_b96 v[120:122], v1 offset:5232
	v_fmac_f32_e32 v70, v55, v101
	v_fmac_f32_e32 v71, v52, v102
	v_fmac_f32_e32 v72, v53, v103
	s_waitcnt lgkmcnt(10)
	v_fmac_f32_e32 v65, v50, v104
	v_add_f32_e32 v65, v70, v65
	v_add_f32_e32 v66, v71, v72
	v_add_f32_e32 v65, v66, v65
	ds_read_b128 v[100:103], v1 offset:5440
	v_sub_f32_e32 v51, v51, v65
	s_waitcnt lgkmcnt(10)
	v_fma_f32 v65, v58, v108, 0
	v_fma_f32 v70, v0, v109, 0
	v_fma_f32 v71, v4, v110, 0
	v_fma_f32 v72, v5, v111, 0
	ds_read_b128 v[104:107], v1 offset:5456
	s_waitcnt lgkmcnt(10)
	v_fmac_f32_e32 v65, v59, v112
	v_fmac_f32_e32 v70, v60, v113
	v_fmac_f32_e32 v71, v61, v114
	v_fmac_f32_e32 v72, v62, v115
	ds_read_b128 v[108:111], v1 offset:5472
	s_waitcnt lgkmcnt(10)
	v_fmac_f32_e32 v65, v63, v76
	v_fmac_f32_e32 v70, v64, v77
	v_fmac_f32_e32 v71, v56, v78
	v_fmac_f32_e32 v72, v57, v79
	ds_read_b128 v[76:79], v1 offset:5488
	s_waitcnt lgkmcnt(10)
	v_fmac_f32_e32 v65, v54, v116
	v_fmac_f32_e32 v70, v55, v117
	ds_read_b128 v[112:115], v1 offset:5504
	v_fmac_f32_e32 v71, v52, v118
	v_fmac_f32_e32 v72, v53, v119
	s_waitcnt lgkmcnt(10)
	v_fmac_f32_e32 v65, v50, v80
	v_fmac_f32_e32 v70, v51, v81
	v_add_f32_e32 v65, v65, v70
	v_add_f32_e32 v66, v71, v72
	v_add_f32_e32 v65, v66, v65
	ds_read_b128 v[80:83], v1 offset:5712
	v_sub_f32_e32 v48, v48, v65
	s_waitcnt lgkmcnt(10)
	v_fma_f32 v65, v58, v84, 0
	v_fma_f32 v70, v0, v85, 0
	v_fma_f32 v71, v4, v86, 0
	v_fma_f32 v72, v5, v87, 0
	ds_read_b128 v[84:87], v1 offset:5728
	s_waitcnt lgkmcnt(10)
	v_fmac_f32_e32 v65, v59, v88
	v_fmac_f32_e32 v70, v60, v89
	v_fmac_f32_e32 v71, v61, v90
	v_fmac_f32_e32 v72, v62, v91
	ds_read_b128 v[88:91], v1 offset:5744
	s_waitcnt lgkmcnt(10)
	v_fmac_f32_e32 v65, v63, v92
	v_fmac_f32_e32 v70, v64, v93
	v_fmac_f32_e32 v71, v56, v94
	v_fmac_f32_e32 v72, v57, v95
	ds_read_b128 v[92:95], v1 offset:5760
	s_waitcnt lgkmcnt(10)
	v_fmac_f32_e32 v65, v54, v96
	v_fmac_f32_e32 v70, v55, v97
	v_fmac_f32_e32 v71, v52, v98
	ds_read_b128 v[116:119], v1 offset:5776
	v_fmac_f32_e32 v72, v53, v99
	s_waitcnt lgkmcnt(10)
; DI void phaseB1(const Params& p, int l, char* smem) {
;     ...
; #pragma unroll
;       for (int i = 1; i < 64; ++i) {
;         float s0 = 0.f, s1 = 0.f, s2 = 0.f, s3 = 0.f;
; #pragma unroll
;         for (int j4 = 0; j4 < i; j4 += 4) {
;           const float4 a = *(const float4*)(Am + i * 68 + j4);
;           s0 += a.x * x[j4];
;           if (j4 + 1 < i) s1 += a.y * x[j4 + 1];
;           if (j4 + 2 < i) s2 += a.z * x[j4 + 2];
;           if (j4 + 3 < i) s3 += a.w * x[j4 + 3];
;         }
;         x[i] = x[i] - ((s0 + s1) + (s2 + s3));
;       }
	v_fmac_f32_e32 v65, v50, v120
	v_fmac_f32_e32 v70, v51, v121
	v_fmac_f32_e32 v71, v48, v122
	v_add_f32_e32 v65, v65, v70
	v_add_f32_e32 v66, v72, v71
	v_add_f32_e32 v65, v66, v65
	ds_read_b32 v96, v1 offset:5792
	v_sub_f32_e32 v49, v49, v65
	s_waitcnt lgkmcnt(10)
	v_fma_f32 v65, v58, v100, 0
	v_fma_f32 v70, v0, v101, 0
	v_fma_f32 v71, v4, v102, 0
	v_fma_f32 v72, v5, v103, 0
	ds_read_b128 v[100:103], v1 offset:5984
	s_waitcnt lgkmcnt(10)
	v_fmac_f32_e32 v65, v59, v104
	v_fmac_f32_e32 v70, v60, v105
	v_fmac_f32_e32 v71, v61, v106
	v_fmac_f32_e32 v72, v62, v107
	ds_read_b128 v[104:107], v1 offset:6000
	s_waitcnt lgkmcnt(10)
	v_fmac_f32_e32 v65, v63, v108
	v_fmac_f32_e32 v70, v64, v109
	v_fmac_f32_e32 v71, v56, v110
	v_fmac_f32_e32 v72, v57, v111
	ds_read_b128 v[108:111], v1 offset:6016
	s_waitcnt lgkmcnt(10)
	v_fmac_f32_e32 v65, v54, v76
	v_fmac_f32_e32 v70, v55, v77
	v_fmac_f32_e32 v71, v52, v78
	v_fmac_f32_e32 v72, v53, v79
	ds_read_b128 v[76:79], v1 offset:6032
	s_waitcnt lgkmcnt(10)
	v_fmac_f32_e32 v65, v50, v112
	v_fmac_f32_e32 v70, v51, v113
	v_fmac_f32_e32 v71, v48, v114
	v_fmac_f32_e32 v72, v49, v115
	v_add_f32_e32 v65, v65, v70
	v_add_f32_e32 v66, v71, v72
	v_add_f32_e32 v65, v66, v65
	ds_read_b128 v[112:115], v1 offset:6048
	v_sub_f32_e32 v46, v46, v65
	s_waitcnt lgkmcnt(10)
	v_fma_f32 v65, v58, v80, 0
	v_fma_f32 v70, v0, v81, 0
	v_fma_f32 v71, v4, v82, 0
	v_fma_f32 v72, v5, v83, 0
	ds_read_b64 v[80:81], v1 offset:6064
	s_waitcnt lgkmcnt(10)
	v_fmac_f32_e32 v65, v59, v84
	v_fmac_f32_e32 v70, v60, v85
	v_fmac_f32_e32 v71, v61, v86
	v_fmac_f32_e32 v72, v62, v87
	ds_read_b128 v[84:87], v1 offset:6256
	s_waitcnt lgkmcnt(10)
	v_fmac_f32_e32 v65, v63, v88
	v_fmac_f32_e32 v70, v64, v89
	v_fmac_f32_e32 v71, v56, v90
	v_fmac_f32_e32 v72, v57, v91
	ds_read_b128 v[88:91], v1 offset:6272
	s_waitcnt lgkmcnt(10)
	v_fmac_f32_e32 v65, v54, v92
	v_fmac_f32_e32 v70, v55, v93
	v_fmac_f32_e32 v71, v52, v94
	v_fmac_f32_e32 v72, v53, v95
	ds_read_b128 v[92:95], v1 offset:6288
	s_waitcnt lgkmcnt(10)
	v_fmac_f32_e32 v65, v50, v116
	ds_read_b128 v[120:123], v1 offset:6304
	v_fmac_f32_e32 v70, v51, v117
	v_fmac_f32_e32 v71, v48, v118
	v_fmac_f32_e32 v72, v49, v119
	s_waitcnt lgkmcnt(10)
	v_fmac_f32_e32 v65, v46, v96
	v_add_f32_e32 v65, v70, v65
	v_add_f32_e32 v66, v71, v72
	v_add_f32_e32 v65, v66, v65
	ds_read_b128 v[96:99], v1 offset:6320
	v_sub_f32_e32 v47, v47, v65
	s_waitcnt lgkmcnt(10)
	v_fma_f32 v65, v58, v100, 0
	v_fma_f32 v70, v0, v101, 0
	v_fma_f32 v71, v4, v102, 0
	v_fma_f32 v72, v5, v103, 0
	ds_read_b96 v[100:102], v1 offset:6336
	s_waitcnt lgkmcnt(10)
	v_fmac_f32_e32 v65, v59, v104
	v_fmac_f32_e32 v70, v60, v105
	v_fmac_f32_e32 v71, v61, v106
	v_fmac_f32_e32 v72, v62, v107
	ds_read_b128 v[104:107], v1 offset:6528
	s_waitcnt lgkmcnt(10)
	v_fmac_f32_e32 v65, v63, v108
	v_fmac_f32_e32 v70, v64, v109
	v_fmac_f32_e32 v71, v56, v110
	v_fmac_f32_e32 v72, v57, v111
	ds_read_b128 v[108:111], v1 offset:6544
	s_waitcnt lgkmcnt(10)
	v_fmac_f32_e32 v65, v54, v76
	v_fmac_f32_e32 v70, v55, v77
	v_fmac_f32_e32 v71, v52, v78
	v_fmac_f32_e32 v72, v53, v79
	ds_read_b128 v[76:79], v1 offset:6560
	s_waitcnt lgkmcnt(10)
	v_fmac_f32_e32 v65, v50, v112
	v_fmac_f32_e32 v70, v51, v113
	ds_read_b128 v[116:119], v1 offset:6576
	v_fmac_f32_e32 v71, v48, v114
	v_fmac_f32_e32 v72, v49, v115
	s_waitcnt lgkmcnt(10)
	v_fmac_f32_e32 v65, v46, v80
	v_fmac_f32_e32 v70, v47, v81
	v_add_f32_e32 v65, v65, v70
	v_add_f32_e32 v66, v71, v72
	v_add_f32_e32 v65, v66, v65
	ds_read_b128 v[80:83], v1 offset:6592
	v_sub_f32_e32 v44, v44, v65
	s_waitcnt lgkmcnt(10)
	v_fma_f32 v65, v58, v84, 0
	v_fma_f32 v70, v0, v85, 0
	v_fma_f32 v71, v4, v86, 0
	v_fma_f32 v72, v5, v87, 0
	ds_read_b128 v[84:87], v1 offset:6608
	s_waitcnt lgkmcnt(10)
	v_fmac_f32_e32 v65, v59, v88
	v_fmac_f32_e32 v70, v60, v89
	v_fmac_f32_e32 v71, v61, v90
	v_fmac_f32_e32 v72, v62, v91
	ds_read_b128 v[88:91], v1 offset:6800
	s_waitcnt lgkmcnt(10)
	v_fmac_f32_e32 v65, v63, v92
	v_fmac_f32_e32 v70, v64, v93
	v_fmac_f32_e32 v71, v56, v94
	v_fmac_f32_e32 v72, v57, v95
	ds_read_b128 v[92:95], v1 offset:6816
	s_waitcnt lgkmcnt(10)
	v_fmac_f32_e32 v65, v54, v120
	v_fmac_f32_e32 v70, v55, v121
	v_fmac_f32_e32 v71, v52, v122
	v_fmac_f32_e32 v72, v53, v123
	ds_read_b128 v[112:115], v1 offset:6832
	s_waitcnt lgkmcnt(10)
	v_fmac_f32_e32 v65, v50, v96
	v_fmac_f32_e32 v70, v51, v97
	v_fmac_f32_e32 v71, v48, v98
	ds_read_b128 v[120:123], v1 offset:6848
	v_fmac_f32_e32 v72, v49, v99
	s_waitcnt lgkmcnt(10)
	v_fmac_f32_e32 v65, v46, v100
	v_fmac_f32_e32 v70, v47, v101
	v_fmac_f32_e32 v71, v44, v102
	v_add_f32_e32 v65, v65, v70
	v_add_f32_e32 v66, v72, v71
	v_add_f32_e32 v65, v66, v65
	ds_read_b128 v[96:99], v1 offset:6864
	v_sub_f32_e32 v45, v45, v65
	s_waitcnt lgkmcnt(10)
	v_fma_f32 v65, v58, v104, 0
	v_fma_f32 v70, v0, v105, 0
	v_fma_f32 v71, v4, v106, 0
	v_fma_f32 v72, v5, v107, 0
	ds_read_b128 v[100:103], v1 offset:6880
	s_waitcnt lgkmcnt(10)
	v_fmac_f32_e32 v65, v59, v108
	v_fmac_f32_e32 v70, v60, v109
	v_fmac_f32_e32 v71, v61, v110
	v_fmac_f32_e32 v72, v62, v111
	ds_read_b32 v104, v1 offset:6896
	s_waitcnt lgkmcnt(10)
	v_fmac_f32_e32 v65, v63, v76
	v_fmac_f32_e32 v70, v64, v77
	v_fmac_f32_e32 v71, v56, v78
	v_fmac_f32_e32 v72, v57, v79
	ds_read_b128 v[76:79], v1 offset:7072
	s_waitcnt lgkmcnt(10)
	v_fmac_f32_e32 v65, v54, v116
	v_fmac_f32_e32 v70, v55, v117
	v_fmac_f32_e32 v71, v52, v118
	v_fmac_f32_e32 v72, v53, v119
	ds_read_b128 v[108:111], v1 offset:7088
	s_waitcnt lgkmcnt(10)
	v_fmac_f32_e32 v65, v50, v80
	v_fmac_f32_e32 v70, v51, v81
	v_fmac_f32_e32 v71, v48, v82
	v_fmac_f32_e32 v72, v49, v83
	ds_read_b128 v[80:83], v1 offset:7104
	s_waitcnt lgkmcnt(10)
; DI void phaseB1(const Params& p, int l, char* smem) {
;     ...
; #pragma unroll
;       for (int i = 1; i < 64; ++i) {
;         float s0 = 0.f, s1 = 0.f, s2 = 0.f, s3 = 0.f;
; #pragma unroll
;         for (int j4 = 0; j4 < i; j4 += 4) {
;           const float4 a = *(const float4*)(Am + i * 68 + j4);
;           s0 += a.x * x[j4];
;           if (j4 + 1 < i) s1 += a.y * x[j4 + 1];
;           if (j4 + 2 < i) s2 += a.z * x[j4 + 2];
;           if (j4 + 3 < i) s3 += a.w * x[j4 + 3];
;         }
;         x[i] = x[i] - ((s0 + s1) + (s2 + s3));
;       }
	v_fmac_f32_e32 v65, v46, v84
	v_fmac_f32_e32 v70, v47, v85
	v_fmac_f32_e32 v71, v44, v86
	v_fmac_f32_e32 v72, v45, v87
	v_add_f32_e32 v65, v65, v70
	v_add_f32_e32 v66, v71, v72
	v_add_f32_e32 v65, v66, v65
	ds_read_b128 v[84:87], v1 offset:7120
	v_sub_f32_e32 v42, v42, v65
	s_waitcnt lgkmcnt(10)
	v_fma_f32 v65, v58, v88, 0
	v_fma_f32 v70, v0, v89, 0
	v_fma_f32 v71, v4, v90, 0
	v_fma_f32 v72, v5, v91, 0
	ds_read_b128 v[88:91], v1 offset:7136
	s_waitcnt lgkmcnt(10)
	v_fmac_f32_e32 v65, v59, v92
	v_fmac_f32_e32 v70, v60, v93
	v_fmac_f32_e32 v71, v61, v94
	v_fmac_f32_e32 v72, v62, v95
	ds_read_b128 v[92:95], v1 offset:7152
	s_waitcnt lgkmcnt(10)
	v_fmac_f32_e32 v65, v63, v112
	v_fmac_f32_e32 v70, v64, v113
	v_fmac_f32_e32 v71, v56, v114
	v_fmac_f32_e32 v72, v57, v115
	ds_read_b64 v[112:113], v1 offset:7168
	s_waitcnt lgkmcnt(10)
	v_fmac_f32_e32 v65, v54, v120
	v_fmac_f32_e32 v70, v55, v121
	v_fmac_f32_e32 v71, v52, v122
	v_fmac_f32_e32 v72, v53, v123
	ds_read_b128 v[116:119], v1 offset:7344
	s_waitcnt lgkmcnt(10)
	v_fmac_f32_e32 v65, v50, v96
	v_fmac_f32_e32 v70, v51, v97
	v_fmac_f32_e32 v71, v48, v98
	v_fmac_f32_e32 v72, v49, v99
	ds_read_b128 v[96:99], v1 offset:7360
	s_waitcnt lgkmcnt(10)
	v_fmac_f32_e32 v65, v46, v100
	ds_read_b128 v[120:123], v1 offset:7376
	v_fmac_f32_e32 v70, v47, v101
	v_fmac_f32_e32 v71, v44, v102
	v_fmac_f32_e32 v72, v45, v103
	s_waitcnt lgkmcnt(10)
	v_fmac_f32_e32 v65, v42, v104
	v_add_f32_e32 v65, v70, v65
	v_add_f32_e32 v66, v71, v72
	v_add_f32_e32 v65, v66, v65
	ds_read_b128 v[100:103], v1 offset:7392
	v_sub_f32_e32 v43, v43, v65
	s_waitcnt lgkmcnt(10)
	v_fma_f32 v65, v58, v76, 0
	v_fma_f32 v70, v0, v77, 0
	v_fma_f32 v71, v4, v78, 0
	v_fma_f32 v72, v5, v79, 0
	ds_read_b128 v[76:79], v1 offset:7408
	s_waitcnt lgkmcnt(10)
	v_fmac_f32_e32 v65, v59, v108
	v_fmac_f32_e32 v70, v60, v109
	v_fmac_f32_e32 v71, v61, v110
	v_fmac_f32_e32 v72, v62, v111
	ds_read_b128 v[104:107], v1 offset:7424
	s_waitcnt lgkmcnt(10)
	v_fmac_f32_e32 v65, v63, v80
	v_fmac_f32_e32 v70, v64, v81
	v_fmac_f32_e32 v71, v56, v82
	v_fmac_f32_e32 v72, v57, v83
	ds_read_b96 v[80:82], v1 offset:7440
	s_waitcnt lgkmcnt(10)
	v_fmac_f32_e32 v65, v54, v84
	v_fmac_f32_e32 v70, v55, v85
	v_fmac_f32_e32 v71, v52, v86
	v_fmac_f32_e32 v72, v53, v87
	ds_read_b128 v[84:87], v1 offset:7616
	s_waitcnt lgkmcnt(10)
	v_fmac_f32_e32 v65, v50, v88
	v_fmac_f32_e32 v70, v51, v89
	v_fmac_f32_e32 v71, v48, v90
	v_fmac_f32_e32 v72, v49, v91
	ds_read_b128 v[88:91], v1 offset:7632
	s_waitcnt lgkmcnt(10)
	v_fmac_f32_e32 v65, v46, v92
	v_fmac_f32_e32 v70, v47, v93
	ds_read_b128 v[108:111], v1 offset:7648
	v_fmac_f32_e32 v71, v44, v94
	v_fmac_f32_e32 v72, v45, v95
	s_waitcnt lgkmcnt(10)
	v_fmac_f32_e32 v65, v42, v112
	v_fmac_f32_e32 v70, v43, v113
	v_add_f32_e32 v65, v65, v70
	v_add_f32_e32 v66, v71, v72
	v_add_f32_e32 v65, v66, v65
	ds_read_b128 v[92:95], v1 offset:7664
	v_sub_f32_e32 v40, v40, v65
	s_waitcnt lgkmcnt(10)
	v_fma_f32 v65, v58, v116, 0
	v_fma_f32 v70, v0, v117, 0
	v_fma_f32 v71, v4, v118, 0
	v_fma_f32 v72, v5, v119, 0
	ds_read_b128 v[112:115], v1 offset:7680
	s_waitcnt lgkmcnt(10)
	v_fmac_f32_e32 v65, v59, v96
	v_fmac_f32_e32 v70, v60, v97
	v_fmac_f32_e32 v71, v61, v98
	v_fmac_f32_e32 v72, v62, v99
	ds_read_b128 v[96:99], v1 offset:7696
	s_waitcnt lgkmcnt(10)
	v_fmac_f32_e32 v65, v63, v120
	v_fmac_f32_e32 v70, v64, v121
	v_fmac_f32_e32 v71, v56, v122
	v_fmac_f32_e32 v72, v57, v123
	ds_read_b128 v[116:119], v1 offset:7712
	s_waitcnt lgkmcnt(10)
	v_fmac_f32_e32 v65, v54, v100
	v_fmac_f32_e32 v70, v55, v101
	v_fmac_f32_e32 v71, v52, v102
	v_fmac_f32_e32 v72, v53, v103
	ds_read_b128 v[100:103], v1 offset:7888
	s_waitcnt lgkmcnt(10)
	v_fmac_f32_e32 v65, v50, v76
	v_fmac_f32_e32 v70, v51, v77
	v_fmac_f32_e32 v71, v48, v78
	v_fmac_f32_e32 v72, v49, v79
	ds_read_b128 v[76:79], v1 offset:7904
	s_waitcnt lgkmcnt(10)
	v_fmac_f32_e32 v65, v46, v104
	v_fmac_f32_e32 v70, v47, v105
	v_fmac_f32_e32 v71, v44, v106
	ds_read_b128 v[120:123], v1 offset:7920
	v_fmac_f32_e32 v72, v45, v107
	s_waitcnt lgkmcnt(10)
	v_fmac_f32_e32 v65, v42, v80
	v_fmac_f32_e32 v70, v43, v81
	v_fmac_f32_e32 v71, v40, v82
	v_add_f32_e32 v65, v65, v70
	v_add_f32_e32 v66, v72, v71
	v_add_f32_e32 v65, v66, v65
	ds_read_b128 v[80:83], v1 offset:7936
	v_sub_f32_e32 v41, v41, v65
	s_waitcnt lgkmcnt(10)
	v_fma_f32 v65, v58, v84, 0
	v_fma_f32 v70, v0, v85, 0
	v_fma_f32 v71, v4, v86, 0
	v_fma_f32 v72, v5, v87, 0
	ds_read_b128 v[84:87], v1 offset:7952
	s_waitcnt lgkmcnt(10)
	v_fmac_f32_e32 v65, v59, v88
	v_fmac_f32_e32 v70, v60, v89
	v_fmac_f32_e32 v71, v61, v90
	v_fmac_f32_e32 v72, v62, v91
	ds_read_b128 v[88:91], v1 offset:7968
	s_waitcnt lgkmcnt(10)
	v_fmac_f32_e32 v65, v63, v108
	v_fmac_f32_e32 v70, v64, v109
	v_fmac_f32_e32 v71, v56, v110
	v_fmac_f32_e32 v72, v57, v111
	ds_read_b128 v[104:107], v1 offset:7984
	s_waitcnt lgkmcnt(10)
	v_fmac_f32_e32 v65, v54, v92
	v_fmac_f32_e32 v70, v55, v93
	v_fmac_f32_e32 v71, v52, v94
	v_fmac_f32_e32 v72, v53, v95
	ds_read_b32 v92, v1 offset:8000
	s_waitcnt lgkmcnt(10)
	v_fmac_f32_e32 v65, v50, v112
	v_fmac_f32_e32 v70, v51, v113
	v_fmac_f32_e32 v71, v48, v114
	v_fmac_f32_e32 v72, v49, v115
	ds_read_b128 v[108:111], v1 offset:8160
	s_waitcnt lgkmcnt(10)
	v_fmac_f32_e32 v65, v46, v96
	v_fmac_f32_e32 v70, v47, v97
	v_fmac_f32_e32 v71, v44, v98
	v_fmac_f32_e32 v72, v45, v99
	ds_read_b128 v[96:99], v1 offset:8176
	s_waitcnt lgkmcnt(10)
	v_fmac_f32_e32 v65, v42, v116
	v_fmac_f32_e32 v70, v43, v117
	v_fmac_f32_e32 v71, v40, v118
	v_fmac_f32_e32 v72, v41, v119
	v_add_f32_e32 v65, v65, v70
	v_add_f32_e32 v66, v71, v72
	v_add_f32_e32 v65, v66, v65
	ds_read_b128 v[112:115], v1 offset:8192
	v_sub_f32_e32 v38, v38, v65
	s_waitcnt lgkmcnt(10)
; DI void phaseB1(const Params& p, int l, char* smem) {
;     ...
; #pragma unroll
;       for (int i = 1; i < 64; ++i) {
;         float s0 = 0.f, s1 = 0.f, s2 = 0.f, s3 = 0.f;
; #pragma unroll
;         for (int j4 = 0; j4 < i; j4 += 4) {
;           const float4 a = *(const float4*)(Am + i * 68 + j4);
;           s0 += a.x * x[j4];
;           if (j4 + 1 < i) s1 += a.y * x[j4 + 1];
;           if (j4 + 2 < i) s2 += a.z * x[j4 + 2];
;           if (j4 + 3 < i) s3 += a.w * x[j4 + 3];
;         }
;         x[i] = x[i] - ((s0 + s1) + (s2 + s3));
;       }
	v_fma_f32 v65, v58, v100, 0
	v_fma_f32 v70, v0, v101, 0
	v_fma_f32 v71, v4, v102, 0
	v_fma_f32 v72, v5, v103, 0
	ds_read_b128 v[100:103], v1 offset:8208
	s_waitcnt lgkmcnt(10)
	v_fmac_f32_e32 v65, v59, v76
	v_fmac_f32_e32 v70, v60, v77
	v_fmac_f32_e32 v71, v61, v78
	v_fmac_f32_e32 v72, v62, v79
	ds_read_b128 v[76:79], v1 offset:8224
	s_waitcnt lgkmcnt(10)
	v_fmac_f32_e32 v65, v63, v120
	v_fmac_f32_e32 v70, v64, v121
	v_fmac_f32_e32 v71, v56, v122
	v_fmac_f32_e32 v72, v57, v123
	ds_read_b128 v[116:119], v1 offset:8240
	s_waitcnt lgkmcnt(10)
	v_fmac_f32_e32 v65, v54, v80
	v_fmac_f32_e32 v70, v55, v81
	v_fmac_f32_e32 v71, v52, v82
	v_fmac_f32_e32 v72, v53, v83
	ds_read_b128 v[80:83], v1 offset:8256
	s_waitcnt lgkmcnt(10)
	v_fmac_f32_e32 v65, v50, v84
	v_fmac_f32_e32 v70, v51, v85
	v_fmac_f32_e32 v71, v48, v86
	v_fmac_f32_e32 v72, v49, v87
	ds_read_b64 v[84:85], v1 offset:8272
	s_waitcnt lgkmcnt(10)
	v_fmac_f32_e32 v65, v46, v88
	v_fmac_f32_e32 v70, v47, v89
	v_fmac_f32_e32 v71, v44, v90
	v_fmac_f32_e32 v72, v45, v91
	ds_read_b128 v[88:91], v1 offset:8432
	s_waitcnt lgkmcnt(10)
	v_fmac_f32_e32 v65, v42, v104
	ds_read_b128 v[120:123], v1 offset:8448
	v_fmac_f32_e32 v70, v43, v105
	v_fmac_f32_e32 v71, v40, v106
	v_fmac_f32_e32 v72, v41, v107
	s_waitcnt lgkmcnt(10)
	v_fmac_f32_e32 v65, v38, v92
	v_add_f32_e32 v65, v70, v65
	v_add_f32_e32 v66, v71, v72
	v_add_f32_e32 v65, v66, v65
	ds_read_b128 v[92:95], v1 offset:8464
	v_sub_f32_e32 v39, v39, v65
	s_waitcnt lgkmcnt(10)
	v_fma_f32 v65, v58, v108, 0
	v_fma_f32 v70, v0, v109, 0
	v_fma_f32 v71, v4, v110, 0
	v_fma_f32 v72, v5, v111, 0
	ds_read_b128 v[104:107], v1 offset:8480
	s_waitcnt lgkmcnt(10)
	v_fmac_f32_e32 v65, v59, v96
	v_fmac_f32_e32 v70, v60, v97
	v_fmac_f32_e32 v71, v61, v98
	v_fmac_f32_e32 v72, v62, v99
	ds_read_b128 v[96:99], v1 offset:8496
	s_waitcnt lgkmcnt(10)
	v_fmac_f32_e32 v65, v63, v112
	v_fmac_f32_e32 v70, v64, v113
	v_fmac_f32_e32 v71, v56, v114
	v_fmac_f32_e32 v72, v57, v115
	ds_read_b128 v[108:111], v1 offset:8512
	s_waitcnt lgkmcnt(10)
	v_fmac_f32_e32 v65, v54, v100
	v_fmac_f32_e32 v70, v55, v101
	v_fmac_f32_e32 v71, v52, v102
	v_fmac_f32_e32 v72, v53, v103
	ds_read_b128 v[100:103], v1 offset:8528
	s_waitcnt lgkmcnt(10)
	v_fmac_f32_e32 v65, v50, v76
	v_fmac_f32_e32 v70, v51, v77
	v_fmac_f32_e32 v71, v48, v78
	v_fmac_f32_e32 v72, v49, v79
	ds_read_b96 v[76:78], v1 offset:8544
	s_waitcnt lgkmcnt(10)
	v_fmac_f32_e32 v65, v46, v116
	v_fmac_f32_e32 v70, v47, v117
	v_fmac_f32_e32 v71, v44, v118
	v_fmac_f32_e32 v72, v45, v119
	ds_read_b128 v[112:115], v1 offset:8704
	s_waitcnt lgkmcnt(10)
	v_fmac_f32_e32 v65, v42, v80
	v_fmac_f32_e32 v70, v43, v81
	ds_read_b128 v[116:119], v1 offset:8720
	v_fmac_f32_e32 v71, v40, v82
	v_fmac_f32_e32 v72, v41, v83
	s_waitcnt lgkmcnt(10)
	v_fmac_f32_e32 v65, v38, v84
	v_fmac_f32_e32 v70, v39, v85
	v_add_f32_e32 v65, v65, v70
	v_add_f32_e32 v66, v71, v72
	v_add_f32_e32 v65, v66, v65
	ds_read_b128 v[80:83], v1 offset:8736
	v_sub_f32_e32 v36, v36, v65
	s_waitcnt lgkmcnt(10)
	v_fma_f32 v65, v58, v88, 0
	v_fma_f32 v70, v0, v89, 0
	v_fma_f32 v71, v4, v90, 0
	v_fma_f32 v72, v5, v91, 0
	ds_read_b128 v[84:87], v1 offset:8752
	s_waitcnt lgkmcnt(10)
	v_fmac_f32_e32 v65, v59, v120
	v_fmac_f32_e32 v70, v60, v121
	v_fmac_f32_e32 v71, v61, v122
	v_fmac_f32_e32 v72, v62, v123
	ds_read_b128 v[88:91], v1 offset:8768
	s_waitcnt lgkmcnt(10)
	v_fmac_f32_e32 v65, v63, v92
	v_fmac_f32_e32 v70, v64, v93
	v_fmac_f32_e32 v71, v56, v94
	v_fmac_f32_e32 v72, v57, v95
	ds_read_b128 v[92:95], v1 offset:8784
	s_waitcnt lgkmcnt(10)
	v_fmac_f32_e32 v65, v54, v104
	v_fmac_f32_e32 v70, v55, v105
	v_fmac_f32_e32 v71, v52, v106
	v_fmac_f32_e32 v72, v53, v107
	ds_read_b128 v[104:107], v1 offset:8800
	s_waitcnt lgkmcnt(10)
	v_fmac_f32_e32 v65, v50, v96
	v_fmac_f32_e32 v70, v51, v97
	v_fmac_f32_e32 v71, v48, v98
	v_fmac_f32_e32 v72, v49, v99
	ds_read_b128 v[96:99], v1 offset:8816
	s_waitcnt lgkmcnt(10)
	v_fmac_f32_e32 v65, v46, v108
	v_fmac_f32_e32 v70, v47, v109
	v_fmac_f32_e32 v71, v44, v110
	v_fmac_f32_e32 v72, v45, v111
	ds_read_b128 v[108:111], v1 offset:8976
	s_waitcnt lgkmcnt(10)
	v_fmac_f32_e32 v65, v42, v100
	v_fmac_f32_e32 v70, v43, v101
	v_fmac_f32_e32 v71, v40, v102
	ds_read_b128 v[120:123], v1 offset:8992
	v_fmac_f32_e32 v72, v41, v103
	s_waitcnt lgkmcnt(10)
	v_fmac_f32_e32 v65, v38, v76
	v_fmac_f32_e32 v70, v39, v77
	v_fmac_f32_e32 v71, v36, v78
	v_add_f32_e32 v65, v65, v70
	v_add_f32_e32 v66, v72, v71
	v_add_f32_e32 v65, v66, v65
	ds_read_b128 v[76:79], v1 offset:9008
	v_sub_f32_e32 v37, v37, v65
	s_waitcnt lgkmcnt(10)
	v_fma_f32 v65, v58, v112, 0
	v_fma_f32 v70, v0, v113, 0
	v_fma_f32 v71, v4, v114, 0
	v_fma_f32 v72, v5, v115, 0
	ds_read_b128 v[100:103], v1 offset:9024
	s_waitcnt lgkmcnt(10)
	v_fmac_f32_e32 v65, v59, v116
	v_fmac_f32_e32 v70, v60, v117
	v_fmac_f32_e32 v71, v61, v118
	v_fmac_f32_e32 v72, v62, v119
	ds_read_b128 v[112:115], v1 offset:9040
	s_waitcnt lgkmcnt(10)
	v_fmac_f32_e32 v65, v63, v80
	v_fmac_f32_e32 v70, v64, v81
	v_fmac_f32_e32 v71, v56, v82
	v_fmac_f32_e32 v72, v57, v83
	ds_read_b128 v[80:83], v1 offset:9056
	s_waitcnt lgkmcnt(10)
	v_fmac_f32_e32 v65, v54, v84
	v_fmac_f32_e32 v70, v55, v85
	v_fmac_f32_e32 v71, v52, v86
	v_fmac_f32_e32 v72, v53, v87
	ds_read_b128 v[84:87], v1 offset:9072
	s_waitcnt lgkmcnt(10)
	v_fmac_f32_e32 v65, v50, v88
	v_fmac_f32_e32 v70, v51, v89
	v_fmac_f32_e32 v71, v48, v90
	v_fmac_f32_e32 v72, v49, v91
	ds_read_b128 v[88:91], v1 offset:9088
	s_waitcnt lgkmcnt(10)
	v_fmac_f32_e32 v65, v46, v92
	v_fmac_f32_e32 v70, v47, v93
	v_fmac_f32_e32 v71, v44, v94
	v_fmac_f32_e32 v72, v45, v95
	ds_read_b32 v92, v1 offset:9104
	s_waitcnt lgkmcnt(10)
; DI void phaseB1(const Params& p, int l, char* smem) {
;     ...
; #pragma unroll
;       for (int i = 1; i < 64; ++i) {
;         float s0 = 0.f, s1 = 0.f, s2 = 0.f, s3 = 0.f;
; #pragma unroll
;         for (int j4 = 0; j4 < i; j4 += 4) {
;           const float4 a = *(const float4*)(Am + i * 68 + j4);
;           s0 += a.x * x[j4];
;           if (j4 + 1 < i) s1 += a.y * x[j4 + 1];
;           if (j4 + 2 < i) s2 += a.z * x[j4 + 2];
;           if (j4 + 3 < i) s3 += a.w * x[j4 + 3];
;         }
;         x[i] = x[i] - ((s0 + s1) + (s2 + s3));
;       }
	v_fmac_f32_e32 v65, v42, v104
	v_fmac_f32_e32 v70, v43, v105
	v_fmac_f32_e32 v71, v40, v106
	v_fmac_f32_e32 v72, v41, v107
	ds_read_b128 v[104:107], v1 offset:9248
	s_waitcnt lgkmcnt(10)
	v_fmac_f32_e32 v65, v38, v96
	v_fmac_f32_e32 v70, v39, v97
	v_fmac_f32_e32 v71, v36, v98
	v_fmac_f32_e32 v72, v37, v99
	v_add_f32_e32 v65, v65, v70
	v_add_f32_e32 v66, v71, v72
	v_add_f32_e32 v65, v66, v65
	ds_read_b128 v[96:99], v1 offset:9264
	v_sub_f32_e32 v34, v34, v65
	s_waitcnt lgkmcnt(10)
	v_fma_f32 v65, v58, v108, 0
	v_fma_f32 v70, v0, v109, 0
	v_fma_f32 v71, v4, v110, 0
	v_fma_f32 v72, v5, v111, 0
	ds_read_b128 v[108:111], v1 offset:9280
	s_waitcnt lgkmcnt(10)
	v_fmac_f32_e32 v65, v59, v120
	v_fmac_f32_e32 v70, v60, v121
	v_fmac_f32_e32 v71, v61, v122
	v_fmac_f32_e32 v72, v62, v123
	ds_read_b128 v[116:119], v1 offset:9296
	s_waitcnt lgkmcnt(10)
	v_fmac_f32_e32 v65, v63, v76
	v_fmac_f32_e32 v70, v64, v77
	v_fmac_f32_e32 v71, v56, v78
	v_fmac_f32_e32 v72, v57, v79
	ds_read_b128 v[76:79], v1 offset:9312
	s_waitcnt lgkmcnt(10)
	v_fmac_f32_e32 v65, v54, v100
	v_fmac_f32_e32 v70, v55, v101
	v_fmac_f32_e32 v71, v52, v102
	v_fmac_f32_e32 v72, v53, v103
	ds_read_b128 v[100:103], v1 offset:9328
	s_waitcnt lgkmcnt(10)
	v_fmac_f32_e32 v65, v50, v112
	v_fmac_f32_e32 v70, v51, v113
	v_fmac_f32_e32 v71, v48, v114
	v_fmac_f32_e32 v72, v49, v115
	ds_read_b128 v[112:115], v1 offset:9344
	s_waitcnt lgkmcnt(10)
	v_fmac_f32_e32 v65, v46, v80
	v_fmac_f32_e32 v70, v47, v81
	v_fmac_f32_e32 v71, v44, v82
	v_fmac_f32_e32 v72, v45, v83
	ds_read_b128 v[80:83], v1 offset:9360
	s_waitcnt lgkmcnt(10)
	v_fmac_f32_e32 v65, v42, v84
	v_fmac_f32_e32 v70, v43, v85
	v_fmac_f32_e32 v71, v40, v86
	v_fmac_f32_e32 v72, v41, v87
	ds_read_b64 v[84:85], v1 offset:9376
	s_waitcnt lgkmcnt(10)
	v_fmac_f32_e32 v65, v38, v88
	ds_read_b128 v[120:123], v1 offset:9520
	v_fmac_f32_e32 v70, v39, v89
	v_fmac_f32_e32 v71, v36, v90
	v_fmac_f32_e32 v72, v37, v91
	s_waitcnt lgkmcnt(10)
	v_fmac_f32_e32 v65, v34, v92
	v_add_f32_e32 v65, v70, v65
	v_add_f32_e32 v66, v71, v72
	v_add_f32_e32 v65, v66, v65
	ds_read_b128 v[88:91], v1 offset:9536
	v_sub_f32_e32 v35, v35, v65
	s_waitcnt lgkmcnt(10)
	v_fma_f32 v65, v58, v104, 0
	v_fma_f32 v70, v0, v105, 0
	v_fma_f32 v71, v4, v106, 0
	v_fma_f32 v72, v5, v107, 0
	ds_read_b128 v[92:95], v1 offset:9552
	s_waitcnt lgkmcnt(10)
	v_fmac_f32_e32 v65, v59, v96
	v_fmac_f32_e32 v70, v60, v97
	v_fmac_f32_e32 v71, v61, v98
	v_fmac_f32_e32 v72, v62, v99
	ds_read_b128 v[96:99], v1 offset:9568
	s_waitcnt lgkmcnt(10)
	v_fmac_f32_e32 v65, v63, v108
	v_fmac_f32_e32 v70, v64, v109
	v_fmac_f32_e32 v71, v56, v110
	v_fmac_f32_e32 v72, v57, v111
	ds_read_b128 v[104:107], v1 offset:9584
	s_waitcnt lgkmcnt(10)
	v_fmac_f32_e32 v65, v54, v116
	v_fmac_f32_e32 v70, v55, v117
	v_fmac_f32_e32 v71, v52, v118
	v_fmac_f32_e32 v72, v53, v119
	ds_read_b128 v[108:111], v1 offset:9600
	s_waitcnt lgkmcnt(10)
	v_fmac_f32_e32 v65, v50, v76
	v_fmac_f32_e32 v70, v51, v77
	v_fmac_f32_e32 v71, v48, v78
	v_fmac_f32_e32 v72, v49, v79
	ds_read_b128 v[76:79], v1 offset:9616
	s_waitcnt lgkmcnt(10)
	v_fmac_f32_e32 v65, v46, v100
	v_fmac_f32_e32 v70, v47, v101
	v_fmac_f32_e32 v71, v44, v102
	v_fmac_f32_e32 v72, v45, v103
	ds_read_b128 v[100:103], v1 offset:9632
	s_waitcnt lgkmcnt(10)
	v_fmac_f32_e32 v65, v42, v112
	v_fmac_f32_e32 v70, v43, v113
	v_fmac_f32_e32 v71, v40, v114
	v_fmac_f32_e32 v72, v41, v115
	ds_read_b96 v[112:114], v1 offset:9648
	s_waitcnt lgkmcnt(10)
	v_fmac_f32_e32 v65, v38, v80
	v_fmac_f32_e32 v70, v39, v81
	ds_read_b128 v[116:119], v1 offset:9792
	v_fmac_f32_e32 v71, v36, v82
	v_fmac_f32_e32 v72, v37, v83
	s_waitcnt lgkmcnt(10)
	v_fmac_f32_e32 v65, v34, v84
	v_fmac_f32_e32 v70, v35, v85
	v_add_f32_e32 v65, v65, v70
	v_add_f32_e32 v66, v71, v72
	v_add_f32_e32 v65, v66, v65
	ds_read_b128 v[80:83], v1 offset:9808
	v_sub_f32_e32 v32, v32, v65
	s_waitcnt lgkmcnt(10)
	v_fma_f32 v65, v58, v120, 0
	v_fma_f32 v70, v0, v121, 0
	v_fma_f32 v71, v4, v122, 0
	v_fma_f32 v72, v5, v123, 0
	ds_read_b128 v[84:87], v1 offset:9824
	s_waitcnt lgkmcnt(10)
	v_fmac_f32_e32 v65, v59, v88
	v_fmac_f32_e32 v70, v60, v89
	v_fmac_f32_e32 v71, v61, v90
	v_fmac_f32_e32 v72, v62, v91
	ds_read_b128 v[88:91], v1 offset:9840
	s_waitcnt lgkmcnt(10)
	v_fmac_f32_e32 v65, v63, v92
	v_fmac_f32_e32 v70, v64, v93
	v_fmac_f32_e32 v71, v56, v94
	v_fmac_f32_e32 v72, v57, v95
	ds_read_b128 v[92:95], v1 offset:9856
	s_waitcnt lgkmcnt(10)
	v_fmac_f32_e32 v65, v54, v96
	v_fmac_f32_e32 v70, v55, v97
	v_fmac_f32_e32 v71, v52, v98
	v_fmac_f32_e32 v72, v53, v99
	ds_read_b128 v[96:99], v1 offset:9872
	s_waitcnt lgkmcnt(10)
	v_fmac_f32_e32 v65, v50, v104
	v_fmac_f32_e32 v70, v51, v105
	v_fmac_f32_e32 v71, v48, v106
	v_fmac_f32_e32 v72, v49, v107
	ds_read_b128 v[104:107], v1 offset:9888
	s_waitcnt lgkmcnt(10)
	v_fmac_f32_e32 v65, v46, v108
	v_fmac_f32_e32 v70, v47, v109
	v_fmac_f32_e32 v71, v44, v110
	v_fmac_f32_e32 v72, v45, v111
	ds_read_b128 v[108:111], v1 offset:9904
	s_waitcnt lgkmcnt(10)
	v_fmac_f32_e32 v65, v42, v76
	v_fmac_f32_e32 v70, v43, v77
	v_fmac_f32_e32 v71, v40, v78
	v_fmac_f32_e32 v72, v41, v79
	ds_read_b128 v[76:79], v1 offset:9920
	s_waitcnt lgkmcnt(10)
	v_fmac_f32_e32 v65, v38, v100
	v_fmac_f32_e32 v70, v39, v101
	v_fmac_f32_e32 v71, v36, v102
	ds_read_b128 v[120:123], v1 offset:10064
	v_fmac_f32_e32 v72, v37, v103
	s_waitcnt lgkmcnt(10)
	v_fmac_f32_e32 v65, v34, v112
	v_fmac_f32_e32 v70, v35, v113
	v_fmac_f32_e32 v71, v32, v114
	v_add_f32_e32 v65, v65, v70
	v_add_f32_e32 v66, v72, v71
	v_add_f32_e32 v65, v66, v65
	ds_read_b128 v[100:103], v1 offset:10080
	v_sub_f32_e32 v33, v33, v65
	s_waitcnt lgkmcnt(10)
; DI void phaseB1(const Params& p, int l, char* smem) {
;     ...
; #pragma unroll
;       for (int i = 1; i < 64; ++i) {
;         float s0 = 0.f, s1 = 0.f, s2 = 0.f, s3 = 0.f;
; #pragma unroll
;         for (int j4 = 0; j4 < i; j4 += 4) {
;           const float4 a = *(const float4*)(Am + i * 68 + j4);
;           s0 += a.x * x[j4];
;           if (j4 + 1 < i) s1 += a.y * x[j4 + 1];
;           if (j4 + 2 < i) s2 += a.z * x[j4 + 2];
;           if (j4 + 3 < i) s3 += a.w * x[j4 + 3];
;         }
;         x[i] = x[i] - ((s0 + s1) + (s2 + s3));
;       }
	v_fma_f32 v65, v58, v116, 0
	v_fma_f32 v70, v0, v117, 0
	v_fma_f32 v71, v4, v118, 0
	v_fma_f32 v72, v5, v119, 0
	ds_read_b128 v[112:115], v1 offset:10096
	s_waitcnt lgkmcnt(10)
	v_fmac_f32_e32 v65, v59, v80
	v_fmac_f32_e32 v70, v60, v81
	v_fmac_f32_e32 v71, v61, v82
	v_fmac_f32_e32 v72, v62, v83
	ds_read_b128 v[80:83], v1 offset:10112
	s_waitcnt lgkmcnt(10)
	v_fmac_f32_e32 v65, v63, v84
	v_fmac_f32_e32 v70, v64, v85
	v_fmac_f32_e32 v71, v56, v86
	v_fmac_f32_e32 v72, v57, v87
	ds_read_b128 v[84:87], v1 offset:10128
	s_waitcnt lgkmcnt(10)
	v_fmac_f32_e32 v65, v54, v88
	v_fmac_f32_e32 v70, v55, v89
	v_fmac_f32_e32 v71, v52, v90
	v_fmac_f32_e32 v72, v53, v91
	ds_read_b128 v[88:91], v1 offset:10144
	s_waitcnt lgkmcnt(10)
	v_fmac_f32_e32 v65, v50, v92
	v_fmac_f32_e32 v70, v51, v93
	v_fmac_f32_e32 v71, v48, v94
	v_fmac_f32_e32 v72, v49, v95
	ds_read_b128 v[92:95], v1 offset:10160
	s_waitcnt lgkmcnt(10)
	v_fmac_f32_e32 v65, v46, v96
	v_fmac_f32_e32 v70, v47, v97
	v_fmac_f32_e32 v71, v44, v98
	v_fmac_f32_e32 v72, v45, v99
	ds_read_b128 v[96:99], v1 offset:10176
	s_waitcnt lgkmcnt(10)
	v_fmac_f32_e32 v65, v42, v104
	v_fmac_f32_e32 v70, v43, v105
	v_fmac_f32_e32 v71, v40, v106
	v_fmac_f32_e32 v72, v41, v107
	ds_read_b128 v[104:107], v1 offset:10192
	s_waitcnt lgkmcnt(10)
	v_fmac_f32_e32 v65, v38, v108
	v_fmac_f32_e32 v70, v39, v109
	v_fmac_f32_e32 v71, v36, v110
	v_fmac_f32_e32 v72, v37, v111
	ds_read_b32 v108, v1 offset:10208
	s_waitcnt lgkmcnt(10)
	v_fmac_f32_e32 v65, v34, v76
	v_fmac_f32_e32 v70, v35, v77
	v_fmac_f32_e32 v71, v32, v78
	v_fmac_f32_e32 v72, v33, v79
	v_add_f32_e32 v65, v65, v70
	v_add_f32_e32 v66, v71, v72
	v_add_f32_e32 v65, v66, v65
	ds_read_b128 v[76:79], v1 offset:10336
	v_sub_f32_e32 v30, v30, v65
	s_waitcnt lgkmcnt(10)
	v_fma_f32 v65, v58, v120, 0
	v_fma_f32 v70, v0, v121, 0
	v_fma_f32 v71, v4, v122, 0
	v_fma_f32 v72, v5, v123, 0
	ds_read_b128 v[116:119], v1 offset:10352
	s_waitcnt lgkmcnt(10)
	v_fmac_f32_e32 v65, v59, v100
	v_fmac_f32_e32 v70, v60, v101
	v_fmac_f32_e32 v71, v61, v102
	v_fmac_f32_e32 v72, v62, v103
	ds_read_b128 v[100:103], v1 offset:10368
	s_waitcnt lgkmcnt(10)
	v_fmac_f32_e32 v65, v63, v112
	v_fmac_f32_e32 v70, v64, v113
	v_fmac_f32_e32 v71, v56, v114
	v_fmac_f32_e32 v72, v57, v115
	ds_read_b128 v[112:115], v1 offset:10384
	s_waitcnt lgkmcnt(10)
	v_fmac_f32_e32 v65, v54, v80
	v_fmac_f32_e32 v70, v55, v81
	v_fmac_f32_e32 v71, v52, v82
	v_fmac_f32_e32 v72, v53, v83
	ds_read_b128 v[80:83], v1 offset:10400
	s_waitcnt lgkmcnt(10)
	v_fmac_f32_e32 v65, v50, v84
	v_fmac_f32_e32 v70, v51, v85
	v_fmac_f32_e32 v71, v48, v86
	v_fmac_f32_e32 v72, v49, v87
	ds_read_b128 v[84:87], v1 offset:10416
	s_waitcnt lgkmcnt(10)
	v_fmac_f32_e32 v65, v46, v88
	v_fmac_f32_e32 v70, v47, v89
	v_fmac_f32_e32 v71, v44, v90
	v_fmac_f32_e32 v72, v45, v91
	ds_read_b128 v[88:91], v1 offset:10432
	s_waitcnt lgkmcnt(10)
	v_fmac_f32_e32 v65, v42, v92
	v_fmac_f32_e32 v70, v43, v93
	v_fmac_f32_e32 v71, v40, v94
	v_fmac_f32_e32 v72, v41, v95
	ds_read_b128 v[92:95], v1 offset:10448
	s_waitcnt lgkmcnt(10)
	v_fmac_f32_e32 v65, v38, v96
	v_fmac_f32_e32 v70, v39, v97
	v_fmac_f32_e32 v71, v36, v98
	v_fmac_f32_e32 v72, v37, v99
	ds_read_b128 v[96:99], v1 offset:10464
	s_waitcnt lgkmcnt(10)
	v_fmac_f32_e32 v65, v34, v104
	ds_read_b64 v[120:121], v1 offset:10480
	v_fmac_f32_e32 v70, v35, v105
	v_fmac_f32_e32 v71, v32, v106
	v_fmac_f32_e32 v72, v33, v107
	s_waitcnt lgkmcnt(10)
	v_fmac_f32_e32 v65, v30, v108
	v_add_f32_e32 v65, v70, v65
	v_add_f32_e32 v66, v71, v72
	v_add_f32_e32 v65, v66, v65
	ds_read_b128 v[104:107], v1 offset:10608
	v_sub_f32_e32 v31, v31, v65
	s_waitcnt lgkmcnt(10)
	v_fma_f32 v65, v58, v76, 0
	v_fma_f32 v70, v0, v77, 0
	v_fma_f32 v71, v4, v78, 0
	v_fma_f32 v72, v5, v79, 0
	ds_read_b128 v[76:79], v1 offset:10624
	s_waitcnt lgkmcnt(10)
	v_fmac_f32_e32 v65, v59, v116
	v_fmac_f32_e32 v70, v60, v117
	v_fmac_f32_e32 v71, v61, v118
	v_fmac_f32_e32 v72, v62, v119
	ds_read_b128 v[108:111], v1 offset:10640
	s_waitcnt lgkmcnt(10)
	v_fmac_f32_e32 v65, v63, v100
	v_fmac_f32_e32 v70, v64, v101
	v_fmac_f32_e32 v71, v56, v102
	v_fmac_f32_e32 v72, v57, v103
	ds_read_b128 v[100:103], v1 offset:10656
	s_waitcnt lgkmcnt(10)
	v_fmac_f32_e32 v65, v54, v112
	v_fmac_f32_e32 v70, v55, v113
	v_fmac_f32_e32 v71, v52, v114
	v_fmac_f32_e32 v72, v53, v115
	ds_read_b128 v[112:115], v1 offset:10672
	s_waitcnt lgkmcnt(10)
	v_fmac_f32_e32 v65, v50, v80
	v_fmac_f32_e32 v70, v51, v81
	v_fmac_f32_e32 v71, v48, v82
	v_fmac_f32_e32 v72, v49, v83
	ds_read_b128 v[80:83], v1 offset:10688
	s_waitcnt lgkmcnt(10)
	v_fmac_f32_e32 v65, v46, v84
	v_fmac_f32_e32 v70, v47, v85
	v_fmac_f32_e32 v71, v44, v86
	v_fmac_f32_e32 v72, v45, v87
	ds_read_b128 v[84:87], v1 offset:10704
	s_waitcnt lgkmcnt(10)
	v_fmac_f32_e32 v65, v42, v88
	v_fmac_f32_e32 v70, v43, v89
	v_fmac_f32_e32 v71, v40, v90
	v_fmac_f32_e32 v72, v41, v91
	ds_read_b128 v[88:91], v1 offset:10720
	s_waitcnt lgkmcnt(10)
	v_fmac_f32_e32 v65, v38, v92
	v_fmac_f32_e32 v70, v39, v93
	v_fmac_f32_e32 v71, v36, v94
	v_fmac_f32_e32 v72, v37, v95
	ds_read_b128 v[92:95], v1 offset:10736
	s_waitcnt lgkmcnt(10)
	v_fmac_f32_e32 v65, v34, v96
	v_fmac_f32_e32 v70, v35, v97
	ds_read_b96 v[116:118], v1 offset:10752
	v_fmac_f32_e32 v71, v32, v98
	v_fmac_f32_e32 v72, v33, v99
	s_waitcnt lgkmcnt(10)
	v_fmac_f32_e32 v65, v30, v120
	v_fmac_f32_e32 v70, v31, v121
	v_add_f32_e32 v65, v65, v70
	v_add_f32_e32 v66, v71, v72
	v_add_f32_e32 v65, v66, v65
	ds_read_b128 v[96:99], v1 offset:10880
	v_sub_f32_e32 v28, v28, v65
	s_waitcnt lgkmcnt(10)
	v_fma_f32 v65, v58, v104, 0
	v_fma_f32 v70, v0, v105, 0
	v_fma_f32 v71, v4, v106, 0
	v_fma_f32 v72, v5, v107, 0
	ds_read_b128 v[104:107], v1 offset:10896
	s_waitcnt lgkmcnt(10)
; DI void phaseB1(const Params& p, int l, char* smem) {
;     ...
; #pragma unroll
;       for (int i = 1; i < 64; ++i) {
;         float s0 = 0.f, s1 = 0.f, s2 = 0.f, s3 = 0.f;
; #pragma unroll
;         for (int j4 = 0; j4 < i; j4 += 4) {
;           const float4 a = *(const float4*)(Am + i * 68 + j4);
;           s0 += a.x * x[j4];
;           if (j4 + 1 < i) s1 += a.y * x[j4 + 1];
;           if (j4 + 2 < i) s2 += a.z * x[j4 + 2];
;           if (j4 + 3 < i) s3 += a.w * x[j4 + 3];
;         }
;         x[i] = x[i] - ((s0 + s1) + (s2 + s3));
;       }
	v_fmac_f32_e32 v65, v59, v76
	v_fmac_f32_e32 v70, v60, v77
	v_fmac_f32_e32 v71, v61, v78
	v_fmac_f32_e32 v72, v62, v79
	ds_read_b128 v[76:79], v1 offset:10912
	s_waitcnt lgkmcnt(10)
	v_fmac_f32_e32 v65, v63, v108
	v_fmac_f32_e32 v70, v64, v109
	v_fmac_f32_e32 v71, v56, v110
	v_fmac_f32_e32 v72, v57, v111
	ds_read_b128 v[108:111], v1 offset:10928
	s_waitcnt lgkmcnt(10)
	v_fmac_f32_e32 v65, v54, v100
	v_fmac_f32_e32 v70, v55, v101
	v_fmac_f32_e32 v71, v52, v102
	v_fmac_f32_e32 v72, v53, v103
	ds_read_b128 v[100:103], v1 offset:10944
	s_waitcnt lgkmcnt(10)
	v_fmac_f32_e32 v65, v50, v112
	v_fmac_f32_e32 v70, v51, v113
	v_fmac_f32_e32 v71, v48, v114
	v_fmac_f32_e32 v72, v49, v115
	ds_read_b128 v[112:115], v1 offset:10960
	s_waitcnt lgkmcnt(10)
	v_fmac_f32_e32 v65, v46, v80
	v_fmac_f32_e32 v70, v47, v81
	v_fmac_f32_e32 v71, v44, v82
	v_fmac_f32_e32 v72, v45, v83
	ds_read_b128 v[80:83], v1 offset:10976
	s_waitcnt lgkmcnt(10)
	v_fmac_f32_e32 v65, v42, v84
	v_fmac_f32_e32 v70, v43, v85
	v_fmac_f32_e32 v71, v40, v86
	v_fmac_f32_e32 v72, v41, v87
	ds_read_b128 v[84:87], v1 offset:10992
	s_waitcnt lgkmcnt(10)
	v_fmac_f32_e32 v65, v38, v88
	v_fmac_f32_e32 v70, v39, v89
	v_fmac_f32_e32 v71, v36, v90
	v_fmac_f32_e32 v72, v37, v91
	ds_read_b128 v[88:91], v1 offset:11008
	s_waitcnt lgkmcnt(10)
	v_fmac_f32_e32 v65, v34, v92
	v_fmac_f32_e32 v70, v35, v93
	v_fmac_f32_e32 v71, v32, v94
	ds_read_b128 v[120:123], v1 offset:11024
	v_fmac_f32_e32 v72, v33, v95
	s_waitcnt lgkmcnt(10)
	v_fmac_f32_e32 v65, v30, v116
	v_fmac_f32_e32 v70, v31, v117
	v_fmac_f32_e32 v71, v28, v118
	v_add_f32_e32 v65, v65, v70
	v_add_f32_e32 v66, v72, v71
	v_add_f32_e32 v65, v66, v65
	ds_read_b128 v[92:95], v1 offset:11152
	v_sub_f32_e32 v29, v29, v65
	s_waitcnt lgkmcnt(10)
	v_fma_f32 v65, v58, v96, 0
	v_fma_f32 v70, v0, v97, 0
	v_fma_f32 v71, v4, v98, 0
	v_fma_f32 v72, v5, v99, 0
	ds_read_b128 v[96:99], v1 offset:11168
	s_waitcnt lgkmcnt(10)
	v_fmac_f32_e32 v65, v59, v104
	v_fmac_f32_e32 v70, v60, v105
	v_fmac_f32_e32 v71, v61, v106
	v_fmac_f32_e32 v72, v62, v107
	ds_read_b128 v[104:107], v1 offset:11184
	s_waitcnt lgkmcnt(10)
	v_fmac_f32_e32 v65, v63, v76
	v_fmac_f32_e32 v70, v64, v77
	v_fmac_f32_e32 v71, v56, v78
	v_fmac_f32_e32 v72, v57, v79
	ds_read_b128 v[76:79], v1 offset:11200
	s_waitcnt lgkmcnt(10)
	v_fmac_f32_e32 v65, v54, v108
	v_fmac_f32_e32 v70, v55, v109
	v_fmac_f32_e32 v71, v52, v110
	v_fmac_f32_e32 v72, v53, v111
	ds_read_b128 v[108:111], v1 offset:11216
	s_waitcnt lgkmcnt(10)
	v_fmac_f32_e32 v65, v50, v100
	v_fmac_f32_e32 v70, v51, v101
	v_fmac_f32_e32 v71, v48, v102
	v_fmac_f32_e32 v72, v49, v103
	ds_read_b128 v[100:103], v1 offset:11232
	s_waitcnt lgkmcnt(10)
	v_fmac_f32_e32 v65, v46, v112
	v_fmac_f32_e32 v70, v47, v113
	v_fmac_f32_e32 v71, v44, v114
	v_fmac_f32_e32 v72, v45, v115
	ds_read_b128 v[112:115], v1 offset:11248
	s_waitcnt lgkmcnt(10)
	v_fmac_f32_e32 v65, v42, v80
	v_fmac_f32_e32 v70, v43, v81
	v_fmac_f32_e32 v71, v40, v82
	v_fmac_f32_e32 v72, v41, v83
	ds_read_b128 v[80:83], v1 offset:11264
	s_waitcnt lgkmcnt(10)
	v_fmac_f32_e32 v65, v38, v84
	v_fmac_f32_e32 v70, v39, v85
	v_fmac_f32_e32 v71, v36, v86
	v_fmac_f32_e32 v72, v37, v87
	ds_read_b128 v[84:87], v1 offset:11280
	s_waitcnt lgkmcnt(10)
	v_fmac_f32_e32 v65, v34, v88
	v_fmac_f32_e32 v70, v35, v89
	v_fmac_f32_e32 v71, v32, v90
	v_fmac_f32_e32 v72, v33, v91
	ds_read_b128 v[88:91], v1 offset:11296
	s_waitcnt lgkmcnt(10)
	v_fmac_f32_e32 v65, v30, v120
	v_fmac_f32_e32 v70, v31, v121
	v_fmac_f32_e32 v71, v28, v122
	v_fmac_f32_e32 v72, v29, v123
	v_add_f32_e32 v65, v65, v70
	v_add_f32_e32 v66, v71, v72
	v_add_f32_e32 v65, v66, v65
	ds_read_b32 v116, v1 offset:11312
	v_sub_f32_e32 v26, v26, v65
	s_waitcnt lgkmcnt(10)
	v_fma_f32 v65, v58, v92, 0
	v_fma_f32 v70, v0, v93, 0
	v_fma_f32 v71, v4, v94, 0
	v_fma_f32 v72, v5, v95, 0
	ds_read_b128 v[92:95], v1 offset:11424
	s_waitcnt lgkmcnt(10)
	v_fmac_f32_e32 v65, v59, v96
	v_fmac_f32_e32 v70, v60, v97
	v_fmac_f32_e32 v71, v61, v98
	v_fmac_f32_e32 v72, v62, v99
	ds_read_b128 v[96:99], v1 offset:11440
	s_waitcnt lgkmcnt(10)
	v_fmac_f32_e32 v65, v63, v104
	v_fmac_f32_e32 v70, v64, v105
	v_fmac_f32_e32 v71, v56, v106
	v_fmac_f32_e32 v72, v57, v107
	ds_read_b128 v[104:107], v1 offset:11456
	s_waitcnt lgkmcnt(10)
	v_fmac_f32_e32 v65, v54, v76
	v_fmac_f32_e32 v70, v55, v77
	v_fmac_f32_e32 v71, v52, v78
	v_fmac_f32_e32 v72, v53, v79
	ds_read_b128 v[76:79], v1 offset:11472
	s_waitcnt lgkmcnt(10)
	v_fmac_f32_e32 v65, v50, v108
	v_fmac_f32_e32 v70, v51, v109
	v_fmac_f32_e32 v71, v48, v110
	v_fmac_f32_e32 v72, v49, v111
	ds_read_b128 v[108:111], v1 offset:11488
	s_waitcnt lgkmcnt(10)
	v_fmac_f32_e32 v65, v46, v100
	v_fmac_f32_e32 v70, v47, v101
	v_fmac_f32_e32 v71, v44, v102
	v_fmac_f32_e32 v72, v45, v103
	ds_read_b128 v[100:103], v1 offset:11504
	s_waitcnt lgkmcnt(10)
	v_fmac_f32_e32 v65, v42, v112
	v_fmac_f32_e32 v70, v43, v113
	v_fmac_f32_e32 v71, v40, v114
	v_fmac_f32_e32 v72, v41, v115
	ds_read_b128 v[112:115], v1 offset:11520
	s_waitcnt lgkmcnt(10)
	v_fmac_f32_e32 v65, v38, v80
	v_fmac_f32_e32 v70, v39, v81
	v_fmac_f32_e32 v71, v36, v82
	v_fmac_f32_e32 v72, v37, v83
	ds_read_b128 v[80:83], v1 offset:11536
	s_waitcnt lgkmcnt(10)
	v_fmac_f32_e32 v65, v34, v84
	v_fmac_f32_e32 v70, v35, v85
	v_fmac_f32_e32 v71, v32, v86
	v_fmac_f32_e32 v72, v33, v87
	ds_read_b128 v[84:87], v1 offset:11552
	s_waitcnt lgkmcnt(10)
	v_fmac_f32_e32 v65, v30, v88
	ds_read_b128 v[120:123], v1 offset:11568
	v_fmac_f32_e32 v70, v31, v89
	v_fmac_f32_e32 v71, v28, v90
	v_fmac_f32_e32 v72, v29, v91
	s_waitcnt lgkmcnt(10)
; DI void phaseB1(const Params& p, int l, char* smem) {
;     ...
; #pragma unroll
;       for (int i = 1; i < 64; ++i) {
;         float s0 = 0.f, s1 = 0.f, s2 = 0.f, s3 = 0.f;
; #pragma unroll
;         for (int j4 = 0; j4 < i; j4 += 4) {
;           const float4 a = *(const float4*)(Am + i * 68 + j4);
;           s0 += a.x * x[j4];
;           if (j4 + 1 < i) s1 += a.y * x[j4 + 1];
;           if (j4 + 2 < i) s2 += a.z * x[j4 + 2];
;           if (j4 + 3 < i) s3 += a.w * x[j4 + 3];
;         }
;         x[i] = x[i] - ((s0 + s1) + (s2 + s3));
;       }
	v_fmac_f32_e32 v65, v26, v116
	v_add_f32_e32 v65, v70, v65
	v_add_f32_e32 v66, v71, v72
	v_add_f32_e32 v65, v66, v65
	ds_read_b64 v[88:89], v1 offset:11584
	v_sub_f32_e32 v27, v27, v65
	s_waitcnt lgkmcnt(10)
	v_fma_f32 v65, v58, v92, 0
	v_fma_f32 v70, v0, v93, 0
	v_fma_f32 v71, v4, v94, 0
	v_fma_f32 v72, v5, v95, 0
	ds_read_b128 v[92:95], v1 offset:11696
	s_waitcnt lgkmcnt(10)
	v_fmac_f32_e32 v65, v59, v96
	v_fmac_f32_e32 v70, v60, v97
	v_fmac_f32_e32 v71, v61, v98
	v_fmac_f32_e32 v72, v62, v99
	ds_read_b128 v[96:99], v1 offset:11712
	s_waitcnt lgkmcnt(10)
	v_fmac_f32_e32 v65, v63, v104
	v_fmac_f32_e32 v70, v64, v105
	v_fmac_f32_e32 v71, v56, v106
	v_fmac_f32_e32 v72, v57, v107
	ds_read_b128 v[104:107], v1 offset:11728
	s_waitcnt lgkmcnt(10)
	v_fmac_f32_e32 v65, v54, v76
	v_fmac_f32_e32 v70, v55, v77
	v_fmac_f32_e32 v71, v52, v78
	v_fmac_f32_e32 v72, v53, v79
	ds_read_b128 v[76:79], v1 offset:11744
	s_waitcnt lgkmcnt(10)
	v_fmac_f32_e32 v65, v50, v108
	v_fmac_f32_e32 v70, v51, v109
	v_fmac_f32_e32 v71, v48, v110
	v_fmac_f32_e32 v72, v49, v111
	ds_read_b128 v[108:111], v1 offset:11760
	s_waitcnt lgkmcnt(10)
	v_fmac_f32_e32 v65, v46, v100
	v_fmac_f32_e32 v70, v47, v101
	v_fmac_f32_e32 v71, v44, v102
	v_fmac_f32_e32 v72, v45, v103
	ds_read_b128 v[100:103], v1 offset:11776
	s_waitcnt lgkmcnt(10)
	v_fmac_f32_e32 v65, v42, v112
	v_fmac_f32_e32 v70, v43, v113
	v_fmac_f32_e32 v71, v40, v114
	v_fmac_f32_e32 v72, v41, v115
	ds_read_b128 v[112:115], v1 offset:11792
	s_waitcnt lgkmcnt(10)
	v_fmac_f32_e32 v65, v38, v80
	v_fmac_f32_e32 v70, v39, v81
	v_fmac_f32_e32 v71, v36, v82
	v_fmac_f32_e32 v72, v37, v83
	ds_read_b128 v[80:83], v1 offset:11808
	s_waitcnt lgkmcnt(10)
	v_fmac_f32_e32 v65, v34, v84
	v_fmac_f32_e32 v70, v35, v85
	v_fmac_f32_e32 v71, v32, v86
	v_fmac_f32_e32 v72, v33, v87
	ds_read_b128 v[84:87], v1 offset:11824
	s_waitcnt lgkmcnt(10)
	v_fmac_f32_e32 v65, v30, v120
	v_fmac_f32_e32 v70, v31, v121
	ds_read_b128 v[116:119], v1 offset:11840
	v_fmac_f32_e32 v71, v28, v122
	v_fmac_f32_e32 v72, v29, v123
	s_waitcnt lgkmcnt(10)
	v_fmac_f32_e32 v65, v26, v88
	v_fmac_f32_e32 v70, v27, v89
	v_add_f32_e32 v65, v65, v70
	v_add_f32_e32 v66, v71, v72
	v_add_f32_e32 v65, v66, v65
	ds_read_b96 v[88:90], v1 offset:11856
	v_sub_f32_e32 v24, v24, v65
	s_waitcnt lgkmcnt(10)
	v_fma_f32 v65, v58, v92, 0
	v_fma_f32 v70, v0, v93, 0
	v_fma_f32 v71, v4, v94, 0
	v_fma_f32 v72, v5, v95, 0
	ds_read_b128 v[92:95], v1 offset:11968
	s_waitcnt lgkmcnt(10)
	v_fmac_f32_e32 v65, v59, v96
	v_fmac_f32_e32 v70, v60, v97
	v_fmac_f32_e32 v71, v61, v98
	v_fmac_f32_e32 v72, v62, v99
	ds_read_b128 v[96:99], v1 offset:11984
	s_waitcnt lgkmcnt(10)
	v_fmac_f32_e32 v65, v63, v104
	v_fmac_f32_e32 v70, v64, v105
	v_fmac_f32_e32 v71, v56, v106
	v_fmac_f32_e32 v72, v57, v107
	ds_read_b128 v[104:107], v1 offset:12000
	s_waitcnt lgkmcnt(10)
	v_fmac_f32_e32 v65, v54, v76
	v_fmac_f32_e32 v70, v55, v77
	v_fmac_f32_e32 v71, v52, v78
	v_fmac_f32_e32 v72, v53, v79
	ds_read_b128 v[76:79], v1 offset:12016
	s_waitcnt lgkmcnt(10)
	v_fmac_f32_e32 v65, v50, v108
	v_fmac_f32_e32 v70, v51, v109
	v_fmac_f32_e32 v71, v48, v110
	v_fmac_f32_e32 v72, v49, v111
	ds_read_b128 v[108:111], v1 offset:12032
	s_waitcnt lgkmcnt(10)
	v_fmac_f32_e32 v65, v46, v100
	v_fmac_f32_e32 v70, v47, v101
	v_fmac_f32_e32 v71, v44, v102
	v_fmac_f32_e32 v72, v45, v103
	ds_read_b128 v[100:103], v1 offset:12048
	s_waitcnt lgkmcnt(10)
	v_fmac_f32_e32 v65, v42, v112
	v_fmac_f32_e32 v70, v43, v113
	v_fmac_f32_e32 v71, v40, v114
	v_fmac_f32_e32 v72, v41, v115
	ds_read_b128 v[112:115], v1 offset:12064
	s_waitcnt lgkmcnt(10)
	v_fmac_f32_e32 v65, v38, v80
	v_fmac_f32_e32 v70, v39, v81
	v_fmac_f32_e32 v71, v36, v82
	v_fmac_f32_e32 v72, v37, v83
	ds_read_b128 v[80:83], v1 offset:12080
	s_waitcnt lgkmcnt(10)
	v_fmac_f32_e32 v65, v34, v84
	v_fmac_f32_e32 v70, v35, v85
	v_fmac_f32_e32 v71, v32, v86
	v_fmac_f32_e32 v72, v33, v87
	ds_read_b128 v[84:87], v1 offset:12096
	s_waitcnt lgkmcnt(10)
	v_fmac_f32_e32 v65, v30, v116
	v_fmac_f32_e32 v70, v31, v117
	v_fmac_f32_e32 v71, v28, v118
	ds_read_b128 v[120:123], v1 offset:12112
	v_fmac_f32_e32 v72, v29, v119
	s_waitcnt lgkmcnt(10)
	v_fmac_f32_e32 v65, v26, v88
	v_fmac_f32_e32 v70, v27, v89
	v_fmac_f32_e32 v71, v24, v90
	v_add_f32_e32 v65, v65, v70
	v_add_f32_e32 v66, v72, v71
	v_add_f32_e32 v65, v66, v65
	ds_read_b128 v[88:91], v1 offset:12128
	v_sub_f32_e32 v25, v25, v65
	s_waitcnt lgkmcnt(10)
	v_fma_f32 v65, v58, v92, 0
	v_fma_f32 v70, v0, v93, 0
	v_fma_f32 v71, v4, v94, 0
	v_fma_f32 v72, v5, v95, 0
	ds_read_b128 v[92:95], v1 offset:12240
	s_waitcnt lgkmcnt(10)
	v_fmac_f32_e32 v65, v59, v96
	v_fmac_f32_e32 v70, v60, v97
	v_fmac_f32_e32 v71, v61, v98
	v_fmac_f32_e32 v72, v62, v99
	ds_read_b128 v[96:99], v1 offset:12256
	s_waitcnt lgkmcnt(10)
	v_fmac_f32_e32 v65, v63, v104
	v_fmac_f32_e32 v70, v64, v105
	v_fmac_f32_e32 v71, v56, v106
	v_fmac_f32_e32 v72, v57, v107
	ds_read_b128 v[104:107], v1 offset:12272
	s_waitcnt lgkmcnt(10)
	v_fmac_f32_e32 v65, v54, v76
	v_fmac_f32_e32 v70, v55, v77
	v_fmac_f32_e32 v71, v52, v78
	v_fmac_f32_e32 v72, v53, v79
	ds_read_b128 v[76:79], v1 offset:12288
	s_waitcnt lgkmcnt(10)
	v_fmac_f32_e32 v65, v50, v108
	v_fmac_f32_e32 v70, v51, v109
	v_fmac_f32_e32 v71, v48, v110
	v_fmac_f32_e32 v72, v49, v111
	ds_read_b128 v[108:111], v1 offset:12304
	s_waitcnt lgkmcnt(10)
	v_fmac_f32_e32 v65, v46, v100
	v_fmac_f32_e32 v70, v47, v101
	v_fmac_f32_e32 v71, v44, v102
	v_fmac_f32_e32 v72, v45, v103
	ds_read_b128 v[100:103], v1 offset:12320
	s_waitcnt lgkmcnt(10)
	v_fmac_f32_e32 v65, v42, v112
	v_fmac_f32_e32 v70, v43, v113
	v_fmac_f32_e32 v71, v40, v114
	v_fmac_f32_e32 v72, v41, v115
	ds_read_b128 v[112:115], v1 offset:12336
	s_waitcnt lgkmcnt(10)
; DI void phaseB1(const Params& p, int l, char* smem) {
;     ...
; #pragma unroll
;       for (int i = 1; i < 64; ++i) {
;         float s0 = 0.f, s1 = 0.f, s2 = 0.f, s3 = 0.f;
; #pragma unroll
;         for (int j4 = 0; j4 < i; j4 += 4) {
;           const float4 a = *(const float4*)(Am + i * 68 + j4);
;           s0 += a.x * x[j4];
;           if (j4 + 1 < i) s1 += a.y * x[j4 + 1];
;           if (j4 + 2 < i) s2 += a.z * x[j4 + 2];
;           if (j4 + 3 < i) s3 += a.w * x[j4 + 3];
;         }
;         x[i] = x[i] - ((s0 + s1) + (s2 + s3));
;       }
	v_fmac_f32_e32 v65, v38, v80
	v_fmac_f32_e32 v70, v39, v81
	v_fmac_f32_e32 v71, v36, v82
	v_fmac_f32_e32 v72, v37, v83
	ds_read_b128 v[80:83], v1 offset:12352
	s_waitcnt lgkmcnt(10)
	v_fmac_f32_e32 v65, v34, v84
	v_fmac_f32_e32 v70, v35, v85
	v_fmac_f32_e32 v71, v32, v86
	v_fmac_f32_e32 v72, v33, v87
	ds_read_b128 v[84:87], v1 offset:12368
	s_waitcnt lgkmcnt(10)
	v_fmac_f32_e32 v65, v30, v120
	v_fmac_f32_e32 v70, v31, v121
	v_fmac_f32_e32 v71, v28, v122
	v_fmac_f32_e32 v72, v29, v123
	ds_read_b128 v[116:119], v1 offset:12384
	s_waitcnt lgkmcnt(10)
	v_fmac_f32_e32 v65, v26, v88
	v_fmac_f32_e32 v70, v27, v89
	v_fmac_f32_e32 v71, v24, v90
	v_fmac_f32_e32 v72, v25, v91
	v_add_f32_e32 v65, v65, v70
	v_add_f32_e32 v66, v71, v72
	v_add_f32_e32 v65, v66, v65
	ds_read_b128 v[88:91], v1 offset:12400
	v_sub_f32_e32 v22, v22, v65
	s_waitcnt lgkmcnt(10)
	v_fma_f32 v65, v58, v92, 0
	v_fma_f32 v70, v0, v93, 0
	v_fma_f32 v71, v4, v94, 0
	v_fma_f32 v72, v5, v95, 0
	ds_read_b32 v92, v1 offset:12416
	s_waitcnt lgkmcnt(10)
	v_fmac_f32_e32 v65, v59, v96
	v_fmac_f32_e32 v70, v60, v97
	v_fmac_f32_e32 v71, v61, v98
	v_fmac_f32_e32 v72, v62, v99
	ds_read_b128 v[96:99], v1 offset:12512
	s_waitcnt lgkmcnt(10)
	v_fmac_f32_e32 v65, v63, v104
	v_fmac_f32_e32 v70, v64, v105
	v_fmac_f32_e32 v71, v56, v106
	v_fmac_f32_e32 v72, v57, v107
	ds_read_b128 v[104:107], v1 offset:12528
	s_waitcnt lgkmcnt(10)
	v_fmac_f32_e32 v65, v54, v76
	v_fmac_f32_e32 v70, v55, v77
	v_fmac_f32_e32 v71, v52, v78
	v_fmac_f32_e32 v72, v53, v79
	ds_read_b128 v[76:79], v1 offset:12544
	s_waitcnt lgkmcnt(10)
	v_fmac_f32_e32 v65, v50, v108
	v_fmac_f32_e32 v70, v51, v109
	v_fmac_f32_e32 v71, v48, v110
	v_fmac_f32_e32 v72, v49, v111
	ds_read_b128 v[108:111], v1 offset:12560
	s_waitcnt lgkmcnt(10)
	v_fmac_f32_e32 v65, v46, v100
	v_fmac_f32_e32 v70, v47, v101
	v_fmac_f32_e32 v71, v44, v102
	v_fmac_f32_e32 v72, v45, v103
	ds_read_b128 v[100:103], v1 offset:12576
	s_waitcnt lgkmcnt(10)
	v_fmac_f32_e32 v65, v42, v112
	v_fmac_f32_e32 v70, v43, v113
	v_fmac_f32_e32 v71, v40, v114
	v_fmac_f32_e32 v72, v41, v115
	ds_read_b128 v[112:115], v1 offset:12592
	s_waitcnt lgkmcnt(10)
	v_fmac_f32_e32 v65, v38, v80
	v_fmac_f32_e32 v70, v39, v81
	v_fmac_f32_e32 v71, v36, v82
	v_fmac_f32_e32 v72, v37, v83
	ds_read_b128 v[80:83], v1 offset:12608
	s_waitcnt lgkmcnt(10)
	v_fmac_f32_e32 v65, v34, v84
	v_fmac_f32_e32 v70, v35, v85
	v_fmac_f32_e32 v71, v32, v86
	v_fmac_f32_e32 v72, v33, v87
	ds_read_b128 v[84:87], v1 offset:12624
	s_waitcnt lgkmcnt(10)
	v_fmac_f32_e32 v65, v30, v116
	v_fmac_f32_e32 v70, v31, v117
	v_fmac_f32_e32 v71, v28, v118
	v_fmac_f32_e32 v72, v29, v119
	ds_read_b128 v[116:119], v1 offset:12640
	s_waitcnt lgkmcnt(10)
	v_fmac_f32_e32 v65, v26, v88
	ds_read_b128 v[120:123], v1 offset:12656
	v_fmac_f32_e32 v70, v27, v89
	v_fmac_f32_e32 v71, v24, v90
	v_fmac_f32_e32 v72, v25, v91
	s_waitcnt lgkmcnt(10)
	v_fmac_f32_e32 v65, v22, v92
	v_add_f32_e32 v65, v70, v65
	v_add_f32_e32 v66, v71, v72
	v_add_f32_e32 v65, v66, v65
	ds_read_b128 v[88:91], v1 offset:12672
	v_sub_f32_e32 v23, v23, v65
	s_waitcnt lgkmcnt(10)
	v_fma_f32 v65, v58, v96, 0
	v_fma_f32 v70, v0, v97, 0
	v_fma_f32 v71, v4, v98, 0
	v_fma_f32 v72, v5, v99, 0
	ds_read_b64 v[92:93], v1 offset:12688
	s_waitcnt lgkmcnt(10)
	v_fmac_f32_e32 v65, v59, v104
	v_fmac_f32_e32 v70, v60, v105
	v_fmac_f32_e32 v71, v61, v106
	v_fmac_f32_e32 v72, v62, v107
	ds_read_b128 v[96:99], v1 offset:12784
	s_waitcnt lgkmcnt(10)
	v_fmac_f32_e32 v65, v63, v76
	v_fmac_f32_e32 v70, v64, v77
	v_fmac_f32_e32 v71, v56, v78
	v_fmac_f32_e32 v72, v57, v79
	ds_read_b128 v[76:79], v1 offset:12800
	s_waitcnt lgkmcnt(10)
	v_fmac_f32_e32 v65, v54, v108
	v_fmac_f32_e32 v70, v55, v109
	v_fmac_f32_e32 v71, v52, v110
	v_fmac_f32_e32 v72, v53, v111
	ds_read_b128 v[104:107], v1 offset:12816
	s_waitcnt lgkmcnt(10)
	v_fmac_f32_e32 v65, v50, v100
	v_fmac_f32_e32 v70, v51, v101
	v_fmac_f32_e32 v71, v48, v102
	v_fmac_f32_e32 v72, v49, v103
	ds_read_b128 v[100:103], v1 offset:12832
	s_waitcnt lgkmcnt(10)
	v_fmac_f32_e32 v65, v46, v112
	v_fmac_f32_e32 v70, v47, v113
	v_fmac_f32_e32 v71, v44, v114
	v_fmac_f32_e32 v72, v45, v115
	ds_read_b128 v[108:111], v1 offset:12848
	s_waitcnt lgkmcnt(10)
	v_fmac_f32_e32 v65, v42, v80
	v_fmac_f32_e32 v70, v43, v81
	v_fmac_f32_e32 v71, v40, v82
	v_fmac_f32_e32 v72, v41, v83
	ds_read_b128 v[80:83], v1 offset:12864
	s_waitcnt lgkmcnt(10)
	v_fmac_f32_e32 v65, v38, v84
	v_fmac_f32_e32 v70, v39, v85
	v_fmac_f32_e32 v71, v36, v86
	v_fmac_f32_e32 v72, v37, v87
	ds_read_b128 v[84:87], v1 offset:12880
	s_waitcnt lgkmcnt(10)
	v_fmac_f32_e32 v65, v34, v116
	v_fmac_f32_e32 v70, v35, v117
	v_fmac_f32_e32 v71, v32, v118
	v_fmac_f32_e32 v72, v33, v119
	ds_read_b128 v[112:115], v1 offset:12896
	s_waitcnt lgkmcnt(10)
	v_fmac_f32_e32 v65, v30, v120
	v_fmac_f32_e32 v70, v31, v121
	v_fmac_f32_e32 v71, v28, v122
	v_fmac_f32_e32 v72, v29, v123
	ds_read_b128 v[116:119], v1 offset:12912
	s_waitcnt lgkmcnt(10)
	v_fmac_f32_e32 v65, v26, v88
	v_fmac_f32_e32 v70, v27, v89
	ds_read_b128 v[120:123], v1 offset:12928
	v_fmac_f32_e32 v71, v24, v90
	v_fmac_f32_e32 v72, v25, v91
	s_waitcnt lgkmcnt(10)
	v_fmac_f32_e32 v65, v22, v92
	v_fmac_f32_e32 v70, v23, v93
	v_add_f32_e32 v65, v65, v70
	v_add_f32_e32 v66, v71, v72
	v_add_f32_e32 v65, v66, v65
	ds_read_b128 v[88:91], v1 offset:12944
	v_sub_f32_e32 v20, v20, v65
	s_waitcnt lgkmcnt(10)
	v_fma_f32 v65, v58, v96, 0
	v_fma_f32 v70, v0, v97, 0
	v_fma_f32 v71, v4, v98, 0
	v_fma_f32 v72, v5, v99, 0
	ds_read_b96 v[92:94], v1 offset:12960
	s_waitcnt lgkmcnt(10)
	v_fmac_f32_e32 v65, v59, v76
	v_fmac_f32_e32 v70, v60, v77
	v_fmac_f32_e32 v71, v61, v78
	v_fmac_f32_e32 v72, v62, v79
	ds_read_b128 v[76:79], v1 offset:13056
	s_waitcnt lgkmcnt(10)
; DI void phaseB1(const Params& p, int l, char* smem) {
;     ...
; #pragma unroll
;       for (int i = 1; i < 64; ++i) {
;         float s0 = 0.f, s1 = 0.f, s2 = 0.f, s3 = 0.f;
; #pragma unroll
;         for (int j4 = 0; j4 < i; j4 += 4) {
;           const float4 a = *(const float4*)(Am + i * 68 + j4);
;           s0 += a.x * x[j4];
;           if (j4 + 1 < i) s1 += a.y * x[j4 + 1];
;           if (j4 + 2 < i) s2 += a.z * x[j4 + 2];
;           if (j4 + 3 < i) s3 += a.w * x[j4 + 3];
;         }
;         x[i] = x[i] - ((s0 + s1) + (s2 + s3));
;       }
	v_fmac_f32_e32 v65, v63, v104
	v_fmac_f32_e32 v70, v64, v105
	v_fmac_f32_e32 v71, v56, v106
	v_fmac_f32_e32 v72, v57, v107
	ds_read_b128 v[96:99], v1 offset:13072
	s_waitcnt lgkmcnt(10)
	v_fmac_f32_e32 v65, v54, v100
	v_fmac_f32_e32 v70, v55, v101
	v_fmac_f32_e32 v71, v52, v102
	v_fmac_f32_e32 v72, v53, v103
	ds_read_b128 v[100:103], v1 offset:13088
	s_waitcnt lgkmcnt(10)
	v_fmac_f32_e32 v65, v50, v108
	v_fmac_f32_e32 v70, v51, v109
	v_fmac_f32_e32 v71, v48, v110
	v_fmac_f32_e32 v72, v49, v111
	ds_read_b128 v[104:107], v1 offset:13104
	s_waitcnt lgkmcnt(10)
	v_fmac_f32_e32 v65, v46, v80
	v_fmac_f32_e32 v70, v47, v81
	v_fmac_f32_e32 v71, v44, v82
	v_fmac_f32_e32 v72, v45, v83
	ds_read_b128 v[80:83], v1 offset:13120
	s_waitcnt lgkmcnt(10)
	v_fmac_f32_e32 v65, v42, v84
	v_fmac_f32_e32 v70, v43, v85
	v_fmac_f32_e32 v71, v40, v86
	v_fmac_f32_e32 v72, v41, v87
	ds_read_b128 v[84:87], v1 offset:13136
	s_waitcnt lgkmcnt(10)
	v_fmac_f32_e32 v65, v38, v112
	v_fmac_f32_e32 v70, v39, v113
	v_fmac_f32_e32 v71, v36, v114
	v_fmac_f32_e32 v72, v37, v115
	ds_read_b128 v[108:111], v1 offset:13152
	s_waitcnt lgkmcnt(10)
	v_fmac_f32_e32 v65, v34, v116
	v_fmac_f32_e32 v70, v35, v117
	v_fmac_f32_e32 v71, v32, v118
	v_fmac_f32_e32 v72, v33, v119
	ds_read_b128 v[112:115], v1 offset:13168
	s_waitcnt lgkmcnt(10)
	v_fmac_f32_e32 v65, v30, v120
	v_fmac_f32_e32 v70, v31, v121
	v_fmac_f32_e32 v71, v28, v122
	v_fmac_f32_e32 v72, v29, v123
	ds_read_b128 v[116:119], v1 offset:13184
	s_waitcnt lgkmcnt(10)
	v_fmac_f32_e32 v65, v26, v88
	v_fmac_f32_e32 v70, v27, v89
	v_fmac_f32_e32 v71, v24, v90
	ds_read_b128 v[120:123], v1 offset:13200
	v_fmac_f32_e32 v72, v25, v91
	s_waitcnt lgkmcnt(10)
	v_fmac_f32_e32 v65, v22, v92
	v_fmac_f32_e32 v70, v23, v93
	v_fmac_f32_e32 v71, v20, v94
	v_add_f32_e32 v65, v65, v70
	v_add_f32_e32 v66, v72, v71
	v_add_f32_e32 v65, v66, v65
	ds_read_b128 v[88:91], v1 offset:13216
	v_sub_f32_e32 v21, v21, v65
	s_waitcnt lgkmcnt(10)
	v_fma_f32 v65, v58, v76, 0
	v_fma_f32 v70, v0, v77, 0
	v_fma_f32 v71, v4, v78, 0
	v_fma_f32 v72, v5, v79, 0
	ds_read_b128 v[76:79], v1 offset:13232
	s_waitcnt lgkmcnt(10)
	v_fmac_f32_e32 v65, v59, v96
	v_fmac_f32_e32 v70, v60, v97
	v_fmac_f32_e32 v71, v61, v98
	v_fmac_f32_e32 v72, v62, v99
	ds_read_b128 v[92:95], v1 offset:13328
	s_waitcnt lgkmcnt(10)
	v_fmac_f32_e32 v65, v63, v100
	v_fmac_f32_e32 v70, v64, v101
	v_fmac_f32_e32 v71, v56, v102
	v_fmac_f32_e32 v72, v57, v103
	ds_read_b128 v[96:99], v1 offset:13344
	s_waitcnt lgkmcnt(10)
	v_fmac_f32_e32 v65, v54, v104
	v_fmac_f32_e32 v70, v55, v105
	v_fmac_f32_e32 v71, v52, v106
	v_fmac_f32_e32 v72, v53, v107
	ds_read_b128 v[100:103], v1 offset:13360
	s_waitcnt lgkmcnt(10)
	v_fmac_f32_e32 v65, v50, v80
	v_fmac_f32_e32 v70, v51, v81
	v_fmac_f32_e32 v71, v48, v82
	v_fmac_f32_e32 v72, v49, v83
	ds_read_b128 v[80:83], v1 offset:13376
	s_waitcnt lgkmcnt(10)
	v_fmac_f32_e32 v65, v46, v84
	v_fmac_f32_e32 v70, v47, v85
	v_fmac_f32_e32 v71, v44, v86
	v_fmac_f32_e32 v72, v45, v87
	ds_read_b128 v[84:87], v1 offset:13392
	s_waitcnt lgkmcnt(10)
	v_fmac_f32_e32 v65, v42, v108
	v_fmac_f32_e32 v70, v43, v109
	v_fmac_f32_e32 v71, v40, v110
	v_fmac_f32_e32 v72, v41, v111
	ds_read_b128 v[104:107], v1 offset:13408
	s_waitcnt lgkmcnt(10)
	v_fmac_f32_e32 v65, v38, v112
	v_fmac_f32_e32 v70, v39, v113
	v_fmac_f32_e32 v71, v36, v114
	v_fmac_f32_e32 v72, v37, v115
	ds_read_b128 v[108:111], v1 offset:13424
	s_waitcnt lgkmcnt(10)
	v_fmac_f32_e32 v65, v34, v116
	v_fmac_f32_e32 v70, v35, v117
	v_fmac_f32_e32 v71, v32, v118
	v_fmac_f32_e32 v72, v33, v119
	ds_read_b128 v[112:115], v1 offset:13440
	s_waitcnt lgkmcnt(10)
	v_fmac_f32_e32 v65, v30, v120
	v_fmac_f32_e32 v70, v31, v121
	v_fmac_f32_e32 v71, v28, v122
	v_fmac_f32_e32 v72, v29, v123
	ds_read_b128 v[116:119], v1 offset:13456
	s_waitcnt lgkmcnt(10)
	v_fmac_f32_e32 v65, v26, v88
	v_fmac_f32_e32 v70, v27, v89
	v_fmac_f32_e32 v71, v24, v90
	v_fmac_f32_e32 v72, v25, v91
	ds_read_b128 v[88:91], v1 offset:13472
	s_waitcnt lgkmcnt(10)
	v_fmac_f32_e32 v65, v22, v76
	v_fmac_f32_e32 v70, v23, v77
	v_fmac_f32_e32 v71, v20, v78
	v_fmac_f32_e32 v72, v21, v79
	v_add_f32_e32 v65, v65, v70
	v_add_f32_e32 v66, v71, v72
	v_add_f32_e32 v65, v66, v65
	ds_read_b128 v[76:79], v1 offset:13488
	v_sub_f32_e32 v18, v18, v65
	s_waitcnt lgkmcnt(10)
	v_fma_f32 v65, v58, v92, 0
	v_fma_f32 v70, v0, v93, 0
	v_fma_f32 v71, v4, v94, 0
	v_fma_f32 v72, v5, v95, 0
	ds_read_b128 v[92:95], v1 offset:13504
	s_waitcnt lgkmcnt(10)
	v_fmac_f32_e32 v65, v59, v96
	v_fmac_f32_e32 v70, v60, v97
	v_fmac_f32_e32 v71, v61, v98
	v_fmac_f32_e32 v72, v62, v99
	ds_read_b32 v96, v1 offset:13520
	s_waitcnt lgkmcnt(10)
	v_fmac_f32_e32 v65, v63, v100
	v_fmac_f32_e32 v70, v64, v101
	v_fmac_f32_e32 v71, v56, v102
	v_fmac_f32_e32 v72, v57, v103
	ds_read_b128 v[100:103], v1 offset:13600
	s_waitcnt lgkmcnt(10)
	v_fmac_f32_e32 v65, v54, v80
	v_fmac_f32_e32 v70, v55, v81
	v_fmac_f32_e32 v71, v52, v82
	v_fmac_f32_e32 v72, v53, v83
	ds_read_b128 v[80:83], v1 offset:13616
	s_waitcnt lgkmcnt(10)
	v_fmac_f32_e32 v65, v50, v84
	v_fmac_f32_e32 v70, v51, v85
	v_fmac_f32_e32 v71, v48, v86
	v_fmac_f32_e32 v72, v49, v87
	ds_read_b128 v[84:87], v1 offset:13632
	s_waitcnt lgkmcnt(10)
	v_fmac_f32_e32 v65, v46, v104
	v_fmac_f32_e32 v70, v47, v105
	v_fmac_f32_e32 v71, v44, v106
	v_fmac_f32_e32 v72, v45, v107
	ds_read_b128 v[104:107], v1 offset:13648
	s_waitcnt lgkmcnt(10)
	v_fmac_f32_e32 v65, v42, v108
	v_fmac_f32_e32 v70, v43, v109
	v_fmac_f32_e32 v71, v40, v110
	v_fmac_f32_e32 v72, v41, v111
	ds_read_b128 v[108:111], v1 offset:13664
	s_waitcnt lgkmcnt(10)
; DI void phaseB1(const Params& p, int l, char* smem) {
;     ...
; #pragma unroll
;       for (int i = 1; i < 64; ++i) {
;         float s0 = 0.f, s1 = 0.f, s2 = 0.f, s3 = 0.f;
; #pragma unroll
;         for (int j4 = 0; j4 < i; j4 += 4) {
;           const float4 a = *(const float4*)(Am + i * 68 + j4);
;           s0 += a.x * x[j4];
;           if (j4 + 1 < i) s1 += a.y * x[j4 + 1];
;           if (j4 + 2 < i) s2 += a.z * x[j4 + 2];
;           if (j4 + 3 < i) s3 += a.w * x[j4 + 3];
;         }
;         x[i] = x[i] - ((s0 + s1) + (s2 + s3));
;       }
	v_fmac_f32_e32 v65, v38, v112
	v_fmac_f32_e32 v70, v39, v113
	v_fmac_f32_e32 v71, v36, v114
	v_fmac_f32_e32 v72, v37, v115
	ds_read_b128 v[112:115], v1 offset:13680
	s_waitcnt lgkmcnt(10)
	v_fmac_f32_e32 v65, v34, v116
	v_fmac_f32_e32 v70, v35, v117
	v_fmac_f32_e32 v71, v32, v118
	v_fmac_f32_e32 v72, v33, v119
	ds_read_b128 v[116:119], v1 offset:13696
	s_waitcnt lgkmcnt(10)
	v_fmac_f32_e32 v65, v30, v88
	v_fmac_f32_e32 v70, v31, v89
	v_fmac_f32_e32 v71, v28, v90
	v_fmac_f32_e32 v72, v29, v91
	ds_read_b128 v[88:91], v1 offset:13712
	s_waitcnt lgkmcnt(10)
	v_fmac_f32_e32 v65, v26, v76
	v_fmac_f32_e32 v70, v27, v77
	v_fmac_f32_e32 v71, v24, v78
	v_fmac_f32_e32 v72, v25, v79
	ds_read_b128 v[76:79], v1 offset:13728
	s_waitcnt lgkmcnt(10)
	v_fmac_f32_e32 v65, v22, v92
	ds_read_b128 v[120:123], v1 offset:13744
	v_fmac_f32_e32 v70, v23, v93
	v_fmac_f32_e32 v71, v20, v94
	v_fmac_f32_e32 v72, v21, v95
	s_waitcnt lgkmcnt(10)
	v_fmac_f32_e32 v65, v18, v96
	v_add_f32_e32 v65, v70, v65
	v_add_f32_e32 v66, v71, v72
	v_add_f32_e32 v65, v66, v65
	ds_read_b128 v[92:95], v1 offset:13760
	v_sub_f32_e32 v19, v19, v65
	s_waitcnt lgkmcnt(10)
	v_fma_f32 v65, v58, v100, 0
	v_fma_f32 v70, v0, v101, 0
	v_fma_f32 v71, v4, v102, 0
	v_fma_f32 v72, v5, v103, 0
	ds_read_b128 v[96:99], v1 offset:13776
	s_waitcnt lgkmcnt(10)
	v_fmac_f32_e32 v65, v59, v80
	v_fmac_f32_e32 v70, v60, v81
	v_fmac_f32_e32 v71, v61, v82
	v_fmac_f32_e32 v72, v62, v83
	ds_read_b64 v[80:81], v1 offset:13792
	s_waitcnt lgkmcnt(10)
	v_fmac_f32_e32 v65, v63, v84
	v_fmac_f32_e32 v70, v64, v85
	v_fmac_f32_e32 v71, v56, v86
	v_fmac_f32_e32 v72, v57, v87
	ds_read_b128 v[84:87], v1 offset:13872
	s_waitcnt lgkmcnt(10)
	v_fmac_f32_e32 v65, v54, v104
	v_fmac_f32_e32 v70, v55, v105
	v_fmac_f32_e32 v71, v52, v106
	v_fmac_f32_e32 v72, v53, v107
	ds_read_b128 v[100:103], v1 offset:13888
	s_waitcnt lgkmcnt(10)
	v_fmac_f32_e32 v65, v50, v108
	v_fmac_f32_e32 v70, v51, v109
	v_fmac_f32_e32 v71, v48, v110
	v_fmac_f32_e32 v72, v49, v111
	ds_read_b128 v[104:107], v1 offset:13904
	s_waitcnt lgkmcnt(10)
	v_fmac_f32_e32 v65, v46, v112
	v_fmac_f32_e32 v70, v47, v113
	v_fmac_f32_e32 v71, v44, v114
	v_fmac_f32_e32 v72, v45, v115
	ds_read_b128 v[108:111], v1 offset:13920
	s_waitcnt lgkmcnt(10)
	v_fmac_f32_e32 v65, v42, v116
	v_fmac_f32_e32 v70, v43, v117
	v_fmac_f32_e32 v71, v40, v118
	v_fmac_f32_e32 v72, v41, v119
	ds_read_b128 v[112:115], v1 offset:13936
	s_waitcnt lgkmcnt(10)
	v_fmac_f32_e32 v65, v38, v88
	v_fmac_f32_e32 v70, v39, v89
	v_fmac_f32_e32 v71, v36, v90
	v_fmac_f32_e32 v72, v37, v91
	ds_read_b128 v[88:91], v1 offset:13952
	s_waitcnt lgkmcnt(10)
	v_fmac_f32_e32 v65, v34, v76
	v_fmac_f32_e32 v70, v35, v77
	v_fmac_f32_e32 v71, v32, v78
	v_fmac_f32_e32 v72, v33, v79
	ds_read_b128 v[76:79], v1 offset:13968
	s_waitcnt lgkmcnt(10)
	v_fmac_f32_e32 v65, v30, v120
	v_fmac_f32_e32 v70, v31, v121
	v_fmac_f32_e32 v71, v28, v122
	v_fmac_f32_e32 v72, v29, v123
	ds_read_b128 v[116:119], v1 offset:13984
	s_waitcnt lgkmcnt(10)
	v_fmac_f32_e32 v65, v26, v92
	v_fmac_f32_e32 v70, v27, v93
	v_fmac_f32_e32 v71, v24, v94
	v_fmac_f32_e32 v72, v25, v95
	ds_read_b128 v[92:95], v1 offset:14000
	s_waitcnt lgkmcnt(10)
	v_fmac_f32_e32 v65, v22, v96
	v_fmac_f32_e32 v70, v23, v97
	ds_read_b128 v[120:123], v1 offset:14016
	v_fmac_f32_e32 v71, v20, v98
	v_fmac_f32_e32 v72, v21, v99
	s_waitcnt lgkmcnt(10)
	v_fmac_f32_e32 v65, v18, v80
	v_fmac_f32_e32 v70, v19, v81
	v_add_f32_e32 v65, v65, v70
	v_add_f32_e32 v66, v71, v72
	v_add_f32_e32 v65, v66, v65
	ds_read_b128 v[80:83], v1 offset:14032
	v_sub_f32_e32 v16, v16, v65
	s_waitcnt lgkmcnt(10)
	v_fma_f32 v65, v58, v84, 0
	v_fma_f32 v70, v0, v85, 0
	v_fma_f32 v71, v4, v86, 0
	v_fma_f32 v72, v5, v87, 0
	ds_read_b128 v[84:87], v1 offset:14048
	s_waitcnt lgkmcnt(10)
	v_fmac_f32_e32 v65, v59, v100
	v_fmac_f32_e32 v70, v60, v101
	v_fmac_f32_e32 v71, v61, v102
	v_fmac_f32_e32 v72, v62, v103
	ds_read_b96 v[96:98], v1 offset:14064
	s_waitcnt lgkmcnt(10)
	v_fmac_f32_e32 v65, v63, v104
	v_fmac_f32_e32 v70, v64, v105
	v_fmac_f32_e32 v71, v56, v106
	v_fmac_f32_e32 v72, v57, v107
	ds_read_b128 v[100:103], v1 offset:14144
	s_waitcnt lgkmcnt(10)
	v_fmac_f32_e32 v65, v54, v108
	v_fmac_f32_e32 v70, v55, v109
	v_fmac_f32_e32 v71, v52, v110
	v_fmac_f32_e32 v72, v53, v111
	ds_read_b128 v[104:107], v1 offset:14160
	s_waitcnt lgkmcnt(10)
	v_fmac_f32_e32 v65, v50, v112
	v_fmac_f32_e32 v70, v51, v113
	v_fmac_f32_e32 v71, v48, v114
	v_fmac_f32_e32 v72, v49, v115
	ds_read_b128 v[108:111], v1 offset:14176
	s_waitcnt lgkmcnt(10)
	v_fmac_f32_e32 v65, v46, v88
	v_fmac_f32_e32 v70, v47, v89
	v_fmac_f32_e32 v71, v44, v90
	v_fmac_f32_e32 v72, v45, v91
	ds_read_b128 v[88:91], v1 offset:14192
	s_waitcnt lgkmcnt(10)
	v_fmac_f32_e32 v65, v42, v76
	v_fmac_f32_e32 v70, v43, v77
	v_fmac_f32_e32 v71, v40, v78
	v_fmac_f32_e32 v72, v41, v79
	ds_read_b128 v[76:79], v1 offset:14208
	s_waitcnt lgkmcnt(10)
	v_fmac_f32_e32 v65, v38, v116
	v_fmac_f32_e32 v70, v39, v117
	v_fmac_f32_e32 v71, v36, v118
	v_fmac_f32_e32 v72, v37, v119
	ds_read_b128 v[112:115], v1 offset:14224
	s_waitcnt lgkmcnt(10)
	v_fmac_f32_e32 v65, v34, v92
	v_fmac_f32_e32 v70, v35, v93
	v_fmac_f32_e32 v71, v32, v94
	v_fmac_f32_e32 v72, v33, v95
	ds_read_b128 v[92:95], v1 offset:14240
	s_waitcnt lgkmcnt(10)
	v_fmac_f32_e32 v65, v30, v120
	v_fmac_f32_e32 v70, v31, v121
	v_fmac_f32_e32 v71, v28, v122
	v_fmac_f32_e32 v72, v29, v123
	ds_read_b128 v[116:119], v1 offset:14256
	s_waitcnt lgkmcnt(10)
	v_fmac_f32_e32 v65, v26, v80
	v_fmac_f32_e32 v70, v27, v81
	v_fmac_f32_e32 v71, v24, v82
	v_fmac_f32_e32 v72, v25, v83
	ds_read_b128 v[80:83], v1 offset:14272
	s_waitcnt lgkmcnt(10)
; DI void phaseB1(const Params& p, int l, char* smem) {
;     ...
; #pragma unroll
;       for (int i = 1; i < 64; ++i) {
;         float s0 = 0.f, s1 = 0.f, s2 = 0.f, s3 = 0.f;
; #pragma unroll
;         for (int j4 = 0; j4 < i; j4 += 4) {
;           const float4 a = *(const float4*)(Am + i * 68 + j4);
;           s0 += a.x * x[j4];
;           if (j4 + 1 < i) s1 += a.y * x[j4 + 1];
;           if (j4 + 2 < i) s2 += a.z * x[j4 + 2];
;           if (j4 + 3 < i) s3 += a.w * x[j4 + 3];
;         }
;         x[i] = x[i] - ((s0 + s1) + (s2 + s3));
;       }
	v_fmac_f32_e32 v65, v22, v84
	v_fmac_f32_e32 v70, v23, v85
	v_fmac_f32_e32 v71, v20, v86
	ds_read_b128 v[120:123], v1 offset:14288
	v_fmac_f32_e32 v72, v21, v87
	s_waitcnt lgkmcnt(10)
	v_fmac_f32_e32 v65, v18, v96
	v_fmac_f32_e32 v70, v19, v97
	v_fmac_f32_e32 v71, v16, v98
	v_add_f32_e32 v65, v65, v70
	v_add_f32_e32 v66, v72, v71
	v_add_f32_e32 v65, v66, v65
	ds_read_b128 v[84:87], v1 offset:14304
	v_sub_f32_e32 v17, v17, v65
	s_waitcnt lgkmcnt(10)
	v_fma_f32 v65, v58, v100, 0
	v_fma_f32 v70, v0, v101, 0
	v_fma_f32 v71, v4, v102, 0
	v_fma_f32 v72, v5, v103, 0
	ds_read_b128 v[96:99], v1 offset:14320
	s_waitcnt lgkmcnt(10)
	v_fmac_f32_e32 v65, v59, v104
	v_fmac_f32_e32 v70, v60, v105
	v_fmac_f32_e32 v71, v61, v106
	v_fmac_f32_e32 v72, v62, v107
	ds_read_b128 v[100:103], v1 offset:14336
	s_waitcnt lgkmcnt(10)
	v_fmac_f32_e32 v65, v63, v108
	v_fmac_f32_e32 v70, v64, v109
	v_fmac_f32_e32 v71, v56, v110
	v_fmac_f32_e32 v72, v57, v111
	ds_read_b128 v[104:107], v1 offset:14416
	s_waitcnt lgkmcnt(10)
	v_fmac_f32_e32 v65, v54, v88
	v_fmac_f32_e32 v70, v55, v89
	v_fmac_f32_e32 v71, v52, v90
	v_fmac_f32_e32 v72, v53, v91
	ds_read_b128 v[88:91], v1 offset:14432
	s_waitcnt lgkmcnt(10)
	v_fmac_f32_e32 v65, v50, v76
	v_fmac_f32_e32 v70, v51, v77
	v_fmac_f32_e32 v71, v48, v78
	v_fmac_f32_e32 v72, v49, v79
	ds_read_b128 v[76:79], v1 offset:14448
	s_waitcnt lgkmcnt(10)
	v_fmac_f32_e32 v65, v46, v112
	v_fmac_f32_e32 v70, v47, v113
	v_fmac_f32_e32 v71, v44, v114
	v_fmac_f32_e32 v72, v45, v115
	ds_read_b128 v[108:111], v1 offset:14464
	s_waitcnt lgkmcnt(10)
	v_fmac_f32_e32 v65, v42, v92
	v_fmac_f32_e32 v70, v43, v93
	v_fmac_f32_e32 v71, v40, v94
	v_fmac_f32_e32 v72, v41, v95
	ds_read_b128 v[92:95], v1 offset:14480
	s_waitcnt lgkmcnt(10)
	v_fmac_f32_e32 v65, v38, v116
	v_fmac_f32_e32 v70, v39, v117
	v_fmac_f32_e32 v71, v36, v118
	v_fmac_f32_e32 v72, v37, v119
	ds_read_b128 v[112:115], v1 offset:14496
	s_waitcnt lgkmcnt(10)
	v_fmac_f32_e32 v65, v34, v80
	v_fmac_f32_e32 v70, v35, v81
	v_fmac_f32_e32 v71, v32, v82
	v_fmac_f32_e32 v72, v33, v83
	ds_read_b128 v[80:83], v1 offset:14512
	s_waitcnt lgkmcnt(10)
	v_fmac_f32_e32 v65, v30, v120
	v_fmac_f32_e32 v70, v31, v121
	v_fmac_f32_e32 v71, v28, v122
	v_fmac_f32_e32 v72, v29, v123
	ds_read_b128 v[116:119], v1 offset:14528
	s_waitcnt lgkmcnt(10)
	v_fmac_f32_e32 v65, v26, v84
	v_fmac_f32_e32 v70, v27, v85
	v_fmac_f32_e32 v71, v24, v86
	v_fmac_f32_e32 v72, v25, v87
	ds_read_b128 v[84:87], v1 offset:14544
	s_waitcnt lgkmcnt(10)
	v_fmac_f32_e32 v65, v22, v96
	v_fmac_f32_e32 v70, v23, v97
	v_fmac_f32_e32 v71, v20, v98
	v_fmac_f32_e32 v72, v21, v99
	ds_read_b128 v[96:99], v1 offset:14560
	s_waitcnt lgkmcnt(10)
	v_fmac_f32_e32 v65, v18, v100
	v_fmac_f32_e32 v70, v19, v101
	v_fmac_f32_e32 v71, v16, v102
	v_fmac_f32_e32 v72, v17, v103
	v_add_f32_e32 v65, v65, v70
	v_add_f32_e32 v66, v71, v72
	v_add_f32_e32 v65, v66, v65
	ds_read_b128 v[100:103], v1 offset:14576
	v_sub_f32_e32 v14, v14, v65
	s_waitcnt lgkmcnt(10)
	v_fma_f32 v65, v58, v104, 0
	v_fma_f32 v70, v0, v105, 0
	v_fma_f32 v71, v4, v106, 0
	v_fma_f32 v72, v5, v107, 0
	ds_read_b128 v[104:107], v1 offset:14592
	s_waitcnt lgkmcnt(10)
	v_fmac_f32_e32 v65, v59, v88
	v_fmac_f32_e32 v70, v60, v89
	v_fmac_f32_e32 v71, v61, v90
	v_fmac_f32_e32 v72, v62, v91
	ds_read_b128 v[88:91], v1 offset:14608
	s_waitcnt lgkmcnt(10)
	v_fmac_f32_e32 v65, v63, v76
	v_fmac_f32_e32 v70, v64, v77
	v_fmac_f32_e32 v71, v56, v78
	v_fmac_f32_e32 v72, v57, v79
	ds_read_b32 v76, v1 offset:14624
	s_waitcnt lgkmcnt(10)
	v_fmac_f32_e32 v65, v54, v108
	v_fmac_f32_e32 v70, v55, v109
	v_fmac_f32_e32 v71, v52, v110
	v_fmac_f32_e32 v72, v53, v111
	ds_read_b128 v[108:111], v1 offset:14688
	s_waitcnt lgkmcnt(10)
	v_fmac_f32_e32 v65, v50, v92
	v_fmac_f32_e32 v70, v51, v93
	v_fmac_f32_e32 v71, v48, v94
	v_fmac_f32_e32 v72, v49, v95
	ds_read_b128 v[92:95], v1 offset:14704
	s_waitcnt lgkmcnt(10)
	v_fmac_f32_e32 v65, v46, v112
	v_fmac_f32_e32 v70, v47, v113
	v_fmac_f32_e32 v71, v44, v114
	v_fmac_f32_e32 v72, v45, v115
	ds_read_b128 v[112:115], v1 offset:14720
	s_waitcnt lgkmcnt(10)
	v_fmac_f32_e32 v65, v42, v80
	v_fmac_f32_e32 v70, v43, v81
	v_fmac_f32_e32 v71, v40, v82
	v_fmac_f32_e32 v72, v41, v83
	ds_read_b128 v[80:83], v1 offset:14736
	s_waitcnt lgkmcnt(10)
	v_fmac_f32_e32 v65, v38, v116
	v_fmac_f32_e32 v70, v39, v117
	v_fmac_f32_e32 v71, v36, v118
	v_fmac_f32_e32 v72, v37, v119
	ds_read_b128 v[116:119], v1 offset:14752
	s_waitcnt lgkmcnt(10)
	v_fmac_f32_e32 v65, v34, v84
	v_fmac_f32_e32 v70, v35, v85
	v_fmac_f32_e32 v71, v32, v86
	v_fmac_f32_e32 v72, v33, v87
	ds_read_b128 v[84:87], v1 offset:14768
	s_waitcnt lgkmcnt(10)
	v_fmac_f32_e32 v65, v30, v96
	v_fmac_f32_e32 v70, v31, v97
	v_fmac_f32_e32 v71, v28, v98
	v_fmac_f32_e32 v72, v29, v99
	ds_read_b128 v[96:99], v1 offset:14784
	s_waitcnt lgkmcnt(10)
	v_fmac_f32_e32 v65, v26, v100
	v_fmac_f32_e32 v70, v27, v101
	v_fmac_f32_e32 v71, v24, v102
	v_fmac_f32_e32 v72, v25, v103
	ds_read_b128 v[100:103], v1 offset:14800
	s_waitcnt lgkmcnt(10)
	v_fmac_f32_e32 v65, v22, v104
	v_fmac_f32_e32 v70, v23, v105
	v_fmac_f32_e32 v71, v20, v106
	v_fmac_f32_e32 v72, v21, v107
	ds_read_b128 v[104:107], v1 offset:14816
	s_waitcnt lgkmcnt(10)
	v_fmac_f32_e32 v65, v18, v88
	ds_read_b128 v[120:123], v1 offset:14832
	v_fmac_f32_e32 v70, v19, v89
	v_fmac_f32_e32 v71, v16, v90
	v_fmac_f32_e32 v72, v17, v91
	s_waitcnt lgkmcnt(10)
	v_fmac_f32_e32 v65, v14, v76
	v_add_f32_e32 v65, v70, v65
	v_add_f32_e32 v66, v71, v72
	v_add_f32_e32 v65, v66, v65
	ds_read_b128 v[76:79], v1 offset:14848
	v_sub_f32_e32 v15, v15, v65
	s_waitcnt lgkmcnt(10)
; DI void phaseB1(const Params& p, int l, char* smem) {
;     ...
; #pragma unroll
;       for (int i = 1; i < 64; ++i) {
;         float s0 = 0.f, s1 = 0.f, s2 = 0.f, s3 = 0.f;
; #pragma unroll
;         for (int j4 = 0; j4 < i; j4 += 4) {
;           const float4 a = *(const float4*)(Am + i * 68 + j4);
;           s0 += a.x * x[j4];
;           if (j4 + 1 < i) s1 += a.y * x[j4 + 1];
;           if (j4 + 2 < i) s2 += a.z * x[j4 + 2];
;           if (j4 + 3 < i) s3 += a.w * x[j4 + 3];
;         }
;         x[i] = x[i] - ((s0 + s1) + (s2 + s3));
;       }
	v_fma_f32 v65, v58, v108, 0
	v_fma_f32 v70, v0, v109, 0
	v_fma_f32 v71, v4, v110, 0
	v_fma_f32 v72, v5, v111, 0
	ds_read_b128 v[88:91], v1 offset:14864
	s_waitcnt lgkmcnt(10)
	v_fmac_f32_e32 v65, v59, v92
	v_fmac_f32_e32 v70, v60, v93
	v_fmac_f32_e32 v71, v61, v94
	v_fmac_f32_e32 v72, v62, v95
	ds_read_b128 v[92:95], v1 offset:14880
	s_waitcnt lgkmcnt(10)
	v_fmac_f32_e32 v65, v63, v112
	v_fmac_f32_e32 v70, v64, v113
	v_fmac_f32_e32 v71, v56, v114
	v_fmac_f32_e32 v72, v57, v115
	ds_read_b64 v[108:109], v1 offset:14896
	s_waitcnt lgkmcnt(10)
	v_fmac_f32_e32 v65, v54, v80
	v_fmac_f32_e32 v70, v55, v81
	v_fmac_f32_e32 v71, v52, v82
	v_fmac_f32_e32 v72, v53, v83
	ds_read_b128 v[80:83], v1 offset:14960
	s_waitcnt lgkmcnt(10)
	v_fmac_f32_e32 v65, v50, v116
	v_fmac_f32_e32 v70, v51, v117
	v_fmac_f32_e32 v71, v48, v118
	v_fmac_f32_e32 v72, v49, v119
	ds_read_b128 v[112:115], v1 offset:14976
	s_waitcnt lgkmcnt(10)
	v_fmac_f32_e32 v65, v46, v84
	v_fmac_f32_e32 v70, v47, v85
	v_fmac_f32_e32 v71, v44, v86
	v_fmac_f32_e32 v72, v45, v87
	ds_read_b128 v[84:87], v1 offset:14992
	s_waitcnt lgkmcnt(10)
	v_fmac_f32_e32 v65, v42, v96
	v_fmac_f32_e32 v70, v43, v97
	v_fmac_f32_e32 v71, v40, v98
	v_fmac_f32_e32 v72, v41, v99
	ds_read_b128 v[96:99], v1 offset:15008
	s_waitcnt lgkmcnt(10)
	v_fmac_f32_e32 v65, v38, v100
	v_fmac_f32_e32 v70, v39, v101
	v_fmac_f32_e32 v71, v36, v102
	v_fmac_f32_e32 v72, v37, v103
	ds_read_b128 v[100:103], v1 offset:15024
	s_waitcnt lgkmcnt(10)
	v_fmac_f32_e32 v65, v34, v104
	v_fmac_f32_e32 v70, v35, v105
	v_fmac_f32_e32 v71, v32, v106
	v_fmac_f32_e32 v72, v33, v107
	ds_read_b128 v[104:107], v1 offset:15040
	s_waitcnt lgkmcnt(10)
	v_fmac_f32_e32 v65, v30, v120
	v_fmac_f32_e32 v70, v31, v121
	v_fmac_f32_e32 v71, v28, v122
	v_fmac_f32_e32 v72, v29, v123
	ds_read_b128 v[116:119], v1 offset:15056
	s_waitcnt lgkmcnt(10)
	v_fmac_f32_e32 v65, v26, v76
	v_fmac_f32_e32 v70, v27, v77
	v_fmac_f32_e32 v71, v24, v78
	v_fmac_f32_e32 v72, v25, v79
	ds_read_b128 v[76:79], v1 offset:15072
	s_waitcnt lgkmcnt(10)
	v_fmac_f32_e32 v65, v22, v88
	v_fmac_f32_e32 v70, v23, v89
	v_fmac_f32_e32 v71, v20, v90
	v_fmac_f32_e32 v72, v21, v91
	ds_read_b128 v[88:91], v1 offset:15088
	s_waitcnt lgkmcnt(10)
	v_fmac_f32_e32 v65, v18, v92
	v_fmac_f32_e32 v70, v19, v93
	ds_read_b128 v[120:123], v1 offset:15104
	v_fmac_f32_e32 v71, v16, v94
	v_fmac_f32_e32 v72, v17, v95
	s_waitcnt lgkmcnt(10)
	v_fmac_f32_e32 v65, v14, v108
	v_fmac_f32_e32 v70, v15, v109
	v_add_f32_e32 v65, v65, v70
	v_add_f32_e32 v66, v71, v72
	v_add_f32_e32 v65, v66, v65
	ds_read_b128 v[92:95], v1 offset:15120
	v_sub_f32_e32 v12, v12, v65
	s_waitcnt lgkmcnt(10)
	v_fma_f32 v65, v58, v80, 0
	v_fma_f32 v70, v0, v81, 0
	v_fma_f32 v71, v4, v82, 0
	v_fma_f32 v72, v5, v83, 0
	ds_read_b128 v[80:83], v1 offset:15136
	s_waitcnt lgkmcnt(10)
	v_fmac_f32_e32 v65, v59, v112
	v_fmac_f32_e32 v70, v60, v113
	v_fmac_f32_e32 v71, v61, v114
	v_fmac_f32_e32 v72, v62, v115
	ds_read_b128 v[108:111], v1 offset:15152
	s_waitcnt lgkmcnt(10)
	v_fmac_f32_e32 v65, v63, v84
	v_fmac_f32_e32 v70, v64, v85
	v_fmac_f32_e32 v71, v56, v86
	v_fmac_f32_e32 v72, v57, v87
	ds_read_b96 v[84:86], v1 offset:15168
	s_waitcnt lgkmcnt(10)
	v_fmac_f32_e32 v65, v54, v96
	v_fmac_f32_e32 v70, v55, v97
	v_fmac_f32_e32 v71, v52, v98
	v_fmac_f32_e32 v72, v53, v99
	ds_read_b128 v[96:99], v1 offset:15232
	s_waitcnt lgkmcnt(10)
	v_fmac_f32_e32 v65, v50, v100
	v_fmac_f32_e32 v70, v51, v101
	v_fmac_f32_e32 v71, v48, v102
	v_fmac_f32_e32 v72, v49, v103
	ds_read_b128 v[100:103], v1 offset:15248
	s_waitcnt lgkmcnt(10)
	v_fmac_f32_e32 v65, v46, v104
	v_fmac_f32_e32 v70, v47, v105
	v_fmac_f32_e32 v71, v44, v106
	v_fmac_f32_e32 v72, v45, v107
	ds_read_b128 v[104:107], v1 offset:15264
	s_waitcnt lgkmcnt(10)
	v_fmac_f32_e32 v65, v42, v116
	v_fmac_f32_e32 v70, v43, v117
	v_fmac_f32_e32 v71, v40, v118
	v_fmac_f32_e32 v72, v41, v119
	ds_read_b128 v[112:115], v1 offset:15280
	s_waitcnt lgkmcnt(10)
	v_fmac_f32_e32 v65, v38, v76
	v_fmac_f32_e32 v70, v39, v77
	v_fmac_f32_e32 v71, v36, v78
	v_fmac_f32_e32 v72, v37, v79
	ds_read_b128 v[76:79], v1 offset:15296
	s_waitcnt lgkmcnt(10)
	v_fmac_f32_e32 v65, v34, v88
	v_fmac_f32_e32 v70, v35, v89
	v_fmac_f32_e32 v71, v32, v90
	v_fmac_f32_e32 v72, v33, v91
	ds_read_b128 v[88:91], v1 offset:15312
	s_waitcnt lgkmcnt(10)
	v_fmac_f32_e32 v65, v30, v120
	v_fmac_f32_e32 v70, v31, v121
	v_fmac_f32_e32 v71, v28, v122
	v_fmac_f32_e32 v72, v29, v123
	ds_read_b128 v[116:119], v1 offset:15328
	s_waitcnt lgkmcnt(10)
	v_fmac_f32_e32 v65, v26, v92
	v_fmac_f32_e32 v70, v27, v93
	v_fmac_f32_e32 v71, v24, v94
	v_fmac_f32_e32 v72, v25, v95
	ds_read_b128 v[92:95], v1 offset:15344
	s_waitcnt lgkmcnt(10)
	v_fmac_f32_e32 v65, v22, v80
	v_fmac_f32_e32 v70, v23, v81
	v_fmac_f32_e32 v71, v20, v82
	v_fmac_f32_e32 v72, v21, v83
	ds_read_b128 v[80:83], v1 offset:15360
	s_waitcnt lgkmcnt(10)
	v_fmac_f32_e32 v65, v18, v108
	v_fmac_f32_e32 v70, v19, v109
	v_fmac_f32_e32 v71, v16, v110
	ds_read_b128 v[120:123], v1 offset:15376
	v_fmac_f32_e32 v72, v17, v111
	s_waitcnt lgkmcnt(10)
	v_fmac_f32_e32 v65, v14, v84
	v_fmac_f32_e32 v70, v15, v85
	v_fmac_f32_e32 v71, v12, v86
	v_add_f32_e32 v65, v65, v70
	v_add_f32_e32 v66, v72, v71
	v_add_f32_e32 v65, v66, v65
	ds_read_b128 v[84:87], v1 offset:15392
	v_sub_f32_e32 v13, v13, v65
	s_waitcnt lgkmcnt(10)
	v_fma_f32 v65, v58, v96, 0
	v_fma_f32 v70, v0, v97, 0
	v_fma_f32 v71, v4, v98, 0
	v_fma_f32 v72, v5, v99, 0
	ds_read_b128 v[96:99], v1 offset:15408
	s_waitcnt lgkmcnt(10)
	v_fmac_f32_e32 v65, v59, v100
	v_fmac_f32_e32 v70, v60, v101
	v_fmac_f32_e32 v71, v61, v102
	v_fmac_f32_e32 v72, v62, v103
	ds_read_b128 v[100:103], v1 offset:15424
	s_waitcnt lgkmcnt(10)
; DI void phaseB1(const Params& p, int l, char* smem) {
;     ...
; #pragma unroll
;       for (int i = 1; i < 64; ++i) {
;         float s0 = 0.f, s1 = 0.f, s2 = 0.f, s3 = 0.f;
; #pragma unroll
;         for (int j4 = 0; j4 < i; j4 += 4) {
;           const float4 a = *(const float4*)(Am + i * 68 + j4);
;           s0 += a.x * x[j4];
;           if (j4 + 1 < i) s1 += a.y * x[j4 + 1];
;           if (j4 + 2 < i) s2 += a.z * x[j4 + 2];
;           if (j4 + 3 < i) s3 += a.w * x[j4 + 3];
;         }
;         x[i] = x[i] - ((s0 + s1) + (s2 + s3));
;       }
	v_fmac_f32_e32 v65, v63, v104
	v_fmac_f32_e32 v70, v64, v105
	v_fmac_f32_e32 v71, v56, v106
	v_fmac_f32_e32 v72, v57, v107
	ds_read_b128 v[104:107], v1 offset:15440
	s_waitcnt lgkmcnt(10)
	v_fmac_f32_e32 v65, v54, v112
	v_fmac_f32_e32 v70, v55, v113
	v_fmac_f32_e32 v71, v52, v114
	v_fmac_f32_e32 v72, v53, v115
	ds_read_b128 v[108:111], v1 offset:15504
	s_waitcnt lgkmcnt(10)
	v_fmac_f32_e32 v65, v50, v76
	v_fmac_f32_e32 v70, v51, v77
	v_fmac_f32_e32 v71, v48, v78
	v_fmac_f32_e32 v72, v49, v79
	ds_read_b128 v[76:79], v1 offset:15520
	s_waitcnt lgkmcnt(10)
	v_fmac_f32_e32 v65, v46, v88
	v_fmac_f32_e32 v70, v47, v89
	v_fmac_f32_e32 v71, v44, v90
	v_fmac_f32_e32 v72, v45, v91
	ds_read_b128 v[88:91], v1 offset:15536
	s_waitcnt lgkmcnt(10)
	v_fmac_f32_e32 v65, v42, v116
	v_fmac_f32_e32 v70, v43, v117
	v_fmac_f32_e32 v71, v40, v118
	v_fmac_f32_e32 v72, v41, v119
	ds_read_b32 v112, v1 offset:15728
	s_waitcnt lgkmcnt(10)
	v_fmac_f32_e32 v65, v38, v92
	v_fmac_f32_e32 v70, v39, v93
	v_fmac_f32_e32 v71, v36, v94
	v_fmac_f32_e32 v72, v37, v95
	ds_read_b128 v[92:95], v1 offset:15552
	s_waitcnt lgkmcnt(10)
	v_fmac_f32_e32 v65, v34, v80
	v_fmac_f32_e32 v70, v35, v81
	v_fmac_f32_e32 v71, v32, v82
	v_fmac_f32_e32 v72, v33, v83
	ds_read_b128 v[80:83], v1 offset:15568
	s_waitcnt lgkmcnt(10)
	v_fmac_f32_e32 v65, v30, v120
	v_fmac_f32_e32 v70, v31, v121
	v_fmac_f32_e32 v71, v28, v122
	v_fmac_f32_e32 v72, v29, v123
	ds_read_b128 v[116:119], v1 offset:15584
	s_waitcnt lgkmcnt(10)
	v_fmac_f32_e32 v65, v26, v84
	v_fmac_f32_e32 v70, v27, v85
	v_fmac_f32_e32 v71, v24, v86
	v_fmac_f32_e32 v72, v25, v87
	ds_read_b128 v[84:87], v1 offset:15600
	s_waitcnt lgkmcnt(10)
	v_fmac_f32_e32 v65, v22, v96
	v_fmac_f32_e32 v70, v23, v97
	v_fmac_f32_e32 v71, v20, v98
	v_fmac_f32_e32 v72, v21, v99
	ds_read_b128 v[96:99], v1 offset:15616
	s_waitcnt lgkmcnt(10)
	v_fmac_f32_e32 v65, v18, v100
	v_fmac_f32_e32 v70, v19, v101
	v_fmac_f32_e32 v71, v16, v102
	v_fmac_f32_e32 v72, v17, v103
	ds_read_b128 v[100:103], v1 offset:15632
	s_waitcnt lgkmcnt(10)
	v_fmac_f32_e32 v65, v14, v104
	v_fmac_f32_e32 v70, v15, v105
	v_fmac_f32_e32 v71, v12, v106
	v_fmac_f32_e32 v72, v13, v107
	v_add_f32_e32 v65, v65, v70
	v_add_f32_e32 v66, v71, v72
	v_add_f32_e32 v65, v66, v65
	ds_read_b128 v[104:107], v1 offset:15648
	ds_read_b128 v[120:123], v1 offset:15664
	v_sub_f32_e32 v10, v10, v65
	s_waitcnt lgkmcnt(11)
	v_fma_f32 v65, v58, v108, 0
	v_fma_f32 v66, v0, v109, 0
	v_fma_f32 v67, v4, v110, 0
	v_fma_f32 v68, v5, v111, 0
	s_waitcnt lgkmcnt(10)
	v_fmac_f32_e32 v65, v59, v76
	v_fmac_f32_e32 v66, v60, v77
	v_fmac_f32_e32 v67, v61, v78
	v_fmac_f32_e32 v68, v62, v79
	ds_read_b128 v[76:79], v1 offset:15680
	ds_read_b128 v[108:111], v1 offset:15696
	s_waitcnt lgkmcnt(11)
	v_fmac_f32_e32 v65, v63, v88
	v_fmac_f32_e32 v66, v64, v89
	v_fmac_f32_e32 v67, v56, v90
	v_fmac_f32_e32 v68, v57, v91
	ds_read_b128 v[88:91], v1 offset:15712
	s_waitcnt lgkmcnt(10)
	v_fmac_f32_e32 v65, v54, v92
	v_fmac_f32_e32 v66, v55, v93
	v_fmac_f32_e32 v67, v52, v94
	v_fmac_f32_e32 v68, v53, v95
	ds_read_b128 v[92:95], v1 offset:15776
	s_waitcnt lgkmcnt(10)
	v_fmac_f32_e32 v65, v50, v80
	v_fmac_f32_e32 v66, v51, v81
	v_fmac_f32_e32 v67, v48, v82
	v_fmac_f32_e32 v68, v49, v83
	ds_read_b128 v[80:83], v1 offset:15792
	s_waitcnt lgkmcnt(10)
	v_fmac_f32_e32 v65, v46, v116
	v_fmac_f32_e32 v66, v47, v117
	v_fmac_f32_e32 v67, v44, v118
	v_fmac_f32_e32 v68, v45, v119
	ds_read_b128 v[116:119], v1 offset:15808
	s_waitcnt lgkmcnt(10)
	v_fmac_f32_e32 v65, v42, v84
	v_fmac_f32_e32 v66, v43, v85
	v_fmac_f32_e32 v67, v40, v86
	v_fmac_f32_e32 v68, v41, v87
	ds_read_b128 v[84:87], v1 offset:15824
	s_waitcnt lgkmcnt(10)
	v_fmac_f32_e32 v65, v38, v96
	v_fmac_f32_e32 v66, v39, v97
	v_fmac_f32_e32 v67, v36, v98
	v_fmac_f32_e32 v68, v37, v99
	ds_read_b128 v[96:99], v1 offset:15840
	s_waitcnt lgkmcnt(10)
	v_fmac_f32_e32 v65, v34, v100
	v_fmac_f32_e32 v66, v35, v101
	v_fmac_f32_e32 v67, v32, v102
	v_fmac_f32_e32 v68, v33, v103
	ds_read_b128 v[100:103], v1 offset:15856
	s_waitcnt lgkmcnt(10)
	v_fmac_f32_e32 v65, v30, v104
	v_fmac_f32_e32 v66, v31, v105
	v_fmac_f32_e32 v67, v28, v106
	v_fmac_f32_e32 v68, v29, v107
	ds_read_b128 v[104:107], v1 offset:15872
	s_waitcnt lgkmcnt(10)
	v_fmac_f32_e32 v65, v26, v120
	v_fmac_f32_e32 v66, v27, v121
	v_fmac_f32_e32 v67, v24, v122
	v_fmac_f32_e32 v68, v25, v123
	ds_read_b128 v[120:123], v1 offset:15888
	s_waitcnt lgkmcnt(10)
	v_fmac_f32_e32 v65, v22, v76
	v_fmac_f32_e32 v66, v23, v77
	v_fmac_f32_e32 v67, v20, v78
	v_fmac_f32_e32 v68, v21, v79
	ds_read_b128 v[76:79], v1 offset:15904
	s_waitcnt lgkmcnt(10)
	v_fmac_f32_e32 v65, v18, v108
	v_fmac_f32_e32 v66, v19, v109
	v_fmac_f32_e32 v67, v16, v110
	v_fmac_f32_e32 v68, v17, v111
	ds_read_b128 v[108:111], v1 offset:15920
	s_waitcnt lgkmcnt(10)
	v_fmac_f32_e32 v65, v14, v88
	v_fmac_f32_e32 v66, v15, v89
	v_fmac_f32_e32 v67, v12, v90
	v_fmac_f32_e32 v68, v13, v91
	v_fmac_f32_e32 v65, v10, v112
	v_add_f32_e32 v65, v66, v65
	v_add_f32_e32 v66, v67, v68
	v_add_f32_e32 v65, v66, v65
	ds_read_b128 v[88:91], v1 offset:15936
	ds_read_b128 v[112:115], v1 offset:15952
	v_sub_f32_e32 v11, v11, v65
	s_waitcnt lgkmcnt(11)
	v_fma_f32 v65, v58, v92, 0
	v_fma_f32 v66, v0, v93, 0
	v_fma_f32 v67, v4, v94, 0
	v_fma_f32 v68, v5, v95, 0
	s_waitcnt lgkmcnt(10)
	v_fmac_f32_e32 v65, v59, v80
	v_fmac_f32_e32 v66, v60, v81
	v_fmac_f32_e32 v67, v61, v82
	v_fmac_f32_e32 v68, v62, v83
	ds_read_b128 v[80:83], v1 offset:15968
	s_waitcnt lgkmcnt(10)
	v_fmac_f32_e32 v65, v63, v116
	v_fmac_f32_e32 v66, v64, v117
	v_fmac_f32_e32 v67, v56, v118
	v_fmac_f32_e32 v68, v57, v119
	ds_read_b128 v[92:95], v1 offset:15984
	s_waitcnt lgkmcnt(10)
; DI void phaseB1(const Params& p, int l, char* smem) {
;     ...
; #pragma unroll
;       for (int i = 1; i < 64; ++i) {
;         float s0 = 0.f, s1 = 0.f, s2 = 0.f, s3 = 0.f;
; #pragma unroll
;         for (int j4 = 0; j4 < i; j4 += 4) {
;           const float4 a = *(const float4*)(Am + i * 68 + j4);
;           s0 += a.x * x[j4];
;           if (j4 + 1 < i) s1 += a.y * x[j4 + 1];
;           if (j4 + 2 < i) s2 += a.z * x[j4 + 2];
;           if (j4 + 3 < i) s3 += a.w * x[j4 + 3];
;         }
;         x[i] = x[i] - ((s0 + s1) + (s2 + s3));
;       }
	v_fmac_f32_e32 v65, v54, v84
	v_fmac_f32_e32 v66, v55, v85
	v_fmac_f32_e32 v67, v52, v86
	v_fmac_f32_e32 v68, v53, v87
	ds_read_b64 v[84:85], v1 offset:16000
	s_waitcnt lgkmcnt(10)
	v_fmac_f32_e32 v65, v50, v96
	v_fmac_f32_e32 v66, v51, v97
	v_fmac_f32_e32 v67, v48, v98
	v_fmac_f32_e32 v68, v49, v99
	ds_read_b128 v[96:99], v1 offset:16048
	s_waitcnt lgkmcnt(10)
	v_fmac_f32_e32 v65, v46, v100
	v_fmac_f32_e32 v66, v47, v101
	v_fmac_f32_e32 v67, v44, v102
	v_fmac_f32_e32 v68, v45, v103
	ds_read_b128 v[100:103], v1 offset:16064
	s_waitcnt lgkmcnt(10)
	v_fmac_f32_e32 v65, v42, v104
	v_fmac_f32_e32 v66, v43, v105
	v_fmac_f32_e32 v67, v40, v106
	v_fmac_f32_e32 v68, v41, v107
	ds_read_b128 v[104:107], v1 offset:16080
	s_waitcnt lgkmcnt(10)
	v_fmac_f32_e32 v65, v38, v120
	v_fmac_f32_e32 v66, v39, v121
	v_fmac_f32_e32 v67, v36, v122
	v_fmac_f32_e32 v68, v37, v123
	ds_read_b128 v[116:119], v1 offset:16096
	s_waitcnt lgkmcnt(10)
	v_fmac_f32_e32 v65, v34, v76
	v_fmac_f32_e32 v66, v35, v77
	v_fmac_f32_e32 v67, v32, v78
	v_fmac_f32_e32 v68, v33, v79
	ds_read_b128 v[76:79], v1 offset:16112
	s_waitcnt lgkmcnt(10)
	v_fmac_f32_e32 v65, v30, v108
	v_fmac_f32_e32 v66, v31, v109
	v_fmac_f32_e32 v67, v28, v110
	v_fmac_f32_e32 v68, v29, v111
	ds_read_b128 v[108:111], v1 offset:16128
	s_waitcnt lgkmcnt(10)
	v_fmac_f32_e32 v65, v26, v88
	v_fmac_f32_e32 v66, v27, v89
	v_fmac_f32_e32 v67, v24, v90
	v_fmac_f32_e32 v68, v25, v91
	ds_read_b128 v[88:91], v1 offset:16144
	s_waitcnt lgkmcnt(10)
	v_fmac_f32_e32 v65, v22, v112
	v_fmac_f32_e32 v66, v23, v113
	v_fmac_f32_e32 v67, v20, v114
	v_fmac_f32_e32 v68, v21, v115
	ds_read_b128 v[112:115], v1 offset:16160
	s_waitcnt lgkmcnt(10)
	v_fmac_f32_e32 v65, v18, v80
	v_fmac_f32_e32 v66, v19, v81
	v_fmac_f32_e32 v67, v16, v82
	v_fmac_f32_e32 v68, v17, v83
	ds_read_b128 v[80:83], v1 offset:16176
	s_waitcnt lgkmcnt(10)
	v_fmac_f32_e32 v65, v14, v92
	v_fmac_f32_e32 v66, v15, v93
	ds_read_b128 v[120:123], v1 offset:16192
	v_fmac_f32_e32 v67, v12, v94
	v_fmac_f32_e32 v68, v13, v95
	s_waitcnt lgkmcnt(10)
	v_fmac_f32_e32 v65, v10, v84
	v_fmac_f32_e32 v66, v11, v85
	v_add_f32_e32 v65, v65, v66
	v_add_f32_e32 v66, v67, v68
	v_add_f32_e32 v65, v66, v65
	ds_read_b128 v[84:87], v1 offset:16208
	ds_read_b128 v[92:95], v1 offset:16224
	v_sub_f32_e32 v8, v8, v65
	s_waitcnt lgkmcnt(11)
	v_fma_f32 v65, v58, v96, 0
	v_fma_f32 v66, v0, v97, 0
	v_fma_f32 v67, v4, v98, 0
	v_fma_f32 v68, v5, v99, 0
	s_waitcnt lgkmcnt(10)
	v_fmac_f32_e32 v65, v59, v100
	v_fmac_f32_e32 v66, v60, v101
	v_fmac_f32_e32 v67, v61, v102
	v_fmac_f32_e32 v68, v62, v103
	ds_read_b128 v[96:99], v1 offset:16240
	s_waitcnt lgkmcnt(10)
	v_fmac_f32_e32 v65, v63, v104
	v_fmac_f32_e32 v66, v64, v105
	v_fmac_f32_e32 v67, v56, v106
	v_fmac_f32_e32 v68, v57, v107
	ds_read_b128 v[100:103], v1 offset:16256
	s_waitcnt lgkmcnt(10)
	v_fmac_f32_e32 v65, v54, v116
	v_fmac_f32_e32 v66, v55, v117
	v_fmac_f32_e32 v67, v52, v118
	v_fmac_f32_e32 v68, v53, v119
	ds_read_b96 v[104:106], v1 offset:16272
	s_waitcnt lgkmcnt(10)
	v_fmac_f32_e32 v65, v50, v76
	v_fmac_f32_e32 v66, v51, v77
	v_fmac_f32_e32 v67, v48, v78
	v_fmac_f32_e32 v68, v49, v79
	ds_read_b128 v[76:79], v1 offset:16320
	s_waitcnt lgkmcnt(10)
	v_fmac_f32_e32 v65, v46, v108
	v_fmac_f32_e32 v66, v47, v109
	v_fmac_f32_e32 v67, v44, v110
	v_fmac_f32_e32 v68, v45, v111
	ds_read_b128 v[108:111], v1 offset:16336
	s_waitcnt lgkmcnt(10)
	v_fmac_f32_e32 v65, v42, v88
	v_fmac_f32_e32 v66, v43, v89
	v_fmac_f32_e32 v67, v40, v90
	v_fmac_f32_e32 v68, v41, v91
	ds_read_b128 v[88:91], v1 offset:16352
	s_waitcnt lgkmcnt(10)
	v_fmac_f32_e32 v65, v38, v112
	v_fmac_f32_e32 v66, v39, v113
	v_fmac_f32_e32 v67, v36, v114
	v_fmac_f32_e32 v68, v37, v115
	ds_read_b128 v[112:115], v1 offset:16368
	s_waitcnt lgkmcnt(10)
	v_fmac_f32_e32 v65, v34, v80
	v_fmac_f32_e32 v66, v35, v81
	v_fmac_f32_e32 v67, v32, v82
	v_fmac_f32_e32 v68, v33, v83
	ds_read_b128 v[80:83], v1 offset:16384
	s_waitcnt lgkmcnt(10)
	v_fmac_f32_e32 v65, v30, v120
	v_fmac_f32_e32 v66, v31, v121
	v_fmac_f32_e32 v67, v28, v122
	v_fmac_f32_e32 v68, v29, v123
	ds_read_b128 v[116:119], v1 offset:16400
	s_waitcnt lgkmcnt(10)
	v_fmac_f32_e32 v65, v26, v84
	v_fmac_f32_e32 v66, v27, v85
	v_fmac_f32_e32 v67, v24, v86
	v_fmac_f32_e32 v68, v25, v87
	ds_read_b128 v[84:87], v1 offset:16416
	s_waitcnt lgkmcnt(10)
	v_fmac_f32_e32 v65, v22, v92
	v_fmac_f32_e32 v66, v23, v93
	v_fmac_f32_e32 v67, v20, v94
	v_fmac_f32_e32 v68, v21, v95
	ds_read_b128 v[92:95], v1 offset:16432
	s_waitcnt lgkmcnt(10)
	v_fmac_f32_e32 v65, v18, v96
	v_fmac_f32_e32 v66, v19, v97
	v_fmac_f32_e32 v67, v16, v98
	v_fmac_f32_e32 v68, v17, v99
	ds_read_b128 v[96:99], v1 offset:16448
	s_waitcnt lgkmcnt(10)
	v_fmac_f32_e32 v65, v14, v100
	v_fmac_f32_e32 v66, v15, v101
	v_fmac_f32_e32 v67, v12, v102
	ds_read_b128 v[120:123], v1 offset:16464
	v_fmac_f32_e32 v68, v13, v103
	s_waitcnt lgkmcnt(10)
	v_fmac_f32_e32 v65, v10, v104
	v_fmac_f32_e32 v66, v11, v105
	v_fmac_f32_e32 v67, v8, v106
	v_add_f32_e32 v65, v65, v66
	v_add_f32_e32 v66, v68, v67
	v_add_f32_e32 v65, v66, v65
	ds_read_b128 v[100:103], v1 offset:16480
	ds_read_b128 v[104:107], v1 offset:16496
	v_sub_f32_e32 v9, v9, v65
	s_waitcnt lgkmcnt(11)
	v_fma_f32 v65, v58, v76, 0
	v_fma_f32 v66, v0, v77, 0
	v_fma_f32 v67, v4, v78, 0
	v_fma_f32 v68, v5, v79, 0
	s_waitcnt lgkmcnt(10)
	v_fmac_f32_e32 v65, v59, v108
	v_fmac_f32_e32 v66, v60, v109
	v_fmac_f32_e32 v67, v61, v110
	v_fmac_f32_e32 v68, v62, v111
	ds_read_b128 v[76:79], v1 offset:16512
	s_waitcnt lgkmcnt(10)
	v_fmac_f32_e32 v65, v63, v88
	v_fmac_f32_e32 v66, v64, v89
	v_fmac_f32_e32 v67, v56, v90
	v_fmac_f32_e32 v68, v57, v91
	ds_read_b128 v[88:91], v1 offset:16528
	s_waitcnt lgkmcnt(10)
; DI void phaseB1(const Params& p, int l, char* smem) {
;     ...
; #pragma unroll
;       for (int i = 1; i < 64; ++i) {
;         float s0 = 0.f, s1 = 0.f, s2 = 0.f, s3 = 0.f;
; #pragma unroll
;         for (int j4 = 0; j4 < i; j4 += 4) {
;           const float4 a = *(const float4*)(Am + i * 68 + j4);
;           s0 += a.x * x[j4];
;           if (j4 + 1 < i) s1 += a.y * x[j4 + 1];
;           if (j4 + 2 < i) s2 += a.z * x[j4 + 2];
;           if (j4 + 3 < i) s3 += a.w * x[j4 + 3];
;         }
;         x[i] = x[i] - ((s0 + s1) + (s2 + s3));
;       }
	v_fmac_f32_e32 v65, v54, v112
	v_fmac_f32_e32 v66, v55, v113
	v_fmac_f32_e32 v67, v52, v114
	v_fmac_f32_e32 v68, v53, v115
	ds_read_b128 v[108:111], v1 offset:16544
	s_waitcnt lgkmcnt(10)
	v_fmac_f32_e32 v65, v50, v80
	v_fmac_f32_e32 v66, v51, v81
	v_fmac_f32_e32 v67, v48, v82
	v_fmac_f32_e32 v68, v49, v83
	ds_read_b128 v[80:83], v1 offset:16592
	s_waitcnt lgkmcnt(10)
	v_fmac_f32_e32 v65, v46, v116
	v_fmac_f32_e32 v66, v47, v117
	v_fmac_f32_e32 v67, v44, v118
	v_fmac_f32_e32 v68, v45, v119
	ds_read_b128 v[112:115], v1 offset:16608
	s_waitcnt lgkmcnt(10)
	v_fmac_f32_e32 v65, v42, v84
	v_fmac_f32_e32 v66, v43, v85
	v_fmac_f32_e32 v67, v40, v86
	v_fmac_f32_e32 v68, v41, v87
	ds_read_b128 v[84:87], v1 offset:16624
	s_waitcnt lgkmcnt(10)
	v_fmac_f32_e32 v65, v38, v92
	v_fmac_f32_e32 v66, v39, v93
	v_fmac_f32_e32 v67, v36, v94
	v_fmac_f32_e32 v68, v37, v95
	ds_read_b32 v92, v1 offset:16832
	s_waitcnt lgkmcnt(10)
	v_fmac_f32_e32 v65, v34, v96
	v_fmac_f32_e32 v66, v35, v97
	v_fmac_f32_e32 v67, v32, v98
	v_fmac_f32_e32 v68, v33, v99
	ds_read_b128 v[96:99], v1 offset:16640
	s_waitcnt lgkmcnt(10)
	v_fmac_f32_e32 v65, v30, v120
	v_fmac_f32_e32 v66, v31, v121
	v_fmac_f32_e32 v67, v28, v122
	v_fmac_f32_e32 v68, v29, v123
	ds_read_b128 v[116:119], v1 offset:16656
	s_waitcnt lgkmcnt(10)
	v_fmac_f32_e32 v65, v26, v100
	v_fmac_f32_e32 v66, v27, v101
	v_fmac_f32_e32 v67, v24, v102
	v_fmac_f32_e32 v68, v25, v103
	ds_read_b128 v[100:103], v1 offset:16672
	s_waitcnt lgkmcnt(10)
	v_fmac_f32_e32 v65, v22, v104
	v_fmac_f32_e32 v66, v23, v105
	v_fmac_f32_e32 v67, v20, v106
	v_fmac_f32_e32 v68, v21, v107
	ds_read_b128 v[104:107], v1 offset:16688
	s_waitcnt lgkmcnt(10)
	v_fmac_f32_e32 v65, v18, v76
	v_fmac_f32_e32 v66, v19, v77
	v_fmac_f32_e32 v67, v16, v78
	v_fmac_f32_e32 v68, v17, v79
	ds_read_b128 v[76:79], v1 offset:16704
	s_waitcnt lgkmcnt(10)
	v_fmac_f32_e32 v65, v14, v88
	v_fmac_f32_e32 v66, v15, v89
	v_fmac_f32_e32 v67, v12, v90
	v_fmac_f32_e32 v68, v13, v91
	ds_read_b128 v[88:91], v1 offset:16720
	s_waitcnt lgkmcnt(10)
	v_fmac_f32_e32 v65, v10, v108
	v_fmac_f32_e32 v66, v11, v109
	v_fmac_f32_e32 v67, v8, v110
	v_fmac_f32_e32 v68, v9, v111
	v_add_f32_e32 v65, v65, v66
	v_add_f32_e32 v66, v67, v68
	v_add_f32_e32 v65, v66, v65
	ds_read_b128 v[108:111], v1 offset:16736
	ds_read_b128 v[120:123], v1 offset:16752
	v_sub_f32_e32 v6, v6, v65
	s_waitcnt lgkmcnt(11)
	v_fma_f32 v65, v58, v80, 0
	v_fma_f32 v66, v0, v81, 0
	v_fma_f32 v67, v4, v82, 0
	v_fma_f32 v68, v5, v83, 0
	s_waitcnt lgkmcnt(10)
	v_fmac_f32_e32 v65, v59, v112
	v_fmac_f32_e32 v66, v60, v113
	v_fmac_f32_e32 v67, v61, v114
	v_fmac_f32_e32 v68, v62, v115
	ds_read_b128 v[80:83], v1 offset:16768
	ds_read_b128 v[112:115], v1 offset:16784
	s_waitcnt lgkmcnt(11)
	v_fmac_f32_e32 v65, v63, v84
	v_fmac_f32_e32 v66, v64, v85
	v_fmac_f32_e32 v67, v56, v86
	v_fmac_f32_e32 v68, v57, v87
	ds_read_b128 v[84:87], v1 offset:16800
	s_waitcnt lgkmcnt(10)
	v_fmac_f32_e32 v65, v54, v96
	v_fmac_f32_e32 v66, v55, v97
	v_fmac_f32_e32 v67, v52, v98
	v_fmac_f32_e32 v68, v53, v99
	ds_read_b128 v[96:99], v1 offset:16816
	s_waitcnt lgkmcnt(10)
	v_fmac_f32_e32 v65, v50, v116
	v_fmac_f32_e32 v66, v51, v117
	v_fmac_f32_e32 v67, v48, v118
	v_fmac_f32_e32 v68, v49, v119
	ds_read_b128 v[116:119], v1 offset:16864
	s_waitcnt lgkmcnt(10)
	v_fmac_f32_e32 v65, v46, v100
	v_fmac_f32_e32 v66, v47, v101
	v_fmac_f32_e32 v67, v44, v102
	v_fmac_f32_e32 v68, v45, v103
	ds_read_b128 v[100:103], v1 offset:16880
	s_waitcnt lgkmcnt(10)
	v_fmac_f32_e32 v65, v42, v104
	v_fmac_f32_e32 v66, v43, v105
	v_fmac_f32_e32 v67, v40, v106
	v_fmac_f32_e32 v68, v41, v107
	ds_read_b128 v[104:107], v1 offset:16896
	s_waitcnt lgkmcnt(10)
	v_fmac_f32_e32 v65, v38, v76
	v_fmac_f32_e32 v66, v39, v77
	v_fmac_f32_e32 v67, v36, v78
	v_fmac_f32_e32 v68, v37, v79
	ds_read_b128 v[76:79], v1 offset:16912
	s_waitcnt lgkmcnt(10)
	v_fmac_f32_e32 v65, v34, v88
	v_fmac_f32_e32 v66, v35, v89
	v_fmac_f32_e32 v67, v32, v90
	v_fmac_f32_e32 v68, v33, v91
	ds_read_b128 v[88:91], v1 offset:16928
	s_waitcnt lgkmcnt(10)
	v_fmac_f32_e32 v65, v30, v108
	v_fmac_f32_e32 v66, v31, v109
	v_fmac_f32_e32 v67, v28, v110
	v_fmac_f32_e32 v68, v29, v111
	ds_read_b128 v[108:111], v1 offset:16944
	s_waitcnt lgkmcnt(10)
	v_fmac_f32_e32 v65, v26, v120
	v_fmac_f32_e32 v66, v27, v121
	v_fmac_f32_e32 v67, v24, v122
	v_fmac_f32_e32 v68, v25, v123
	ds_read_b128 v[120:123], v1 offset:16960
	s_waitcnt lgkmcnt(10)
	v_fmac_f32_e32 v65, v22, v80
	v_fmac_f32_e32 v66, v23, v81
	v_fmac_f32_e32 v67, v20, v82
	v_fmac_f32_e32 v68, v21, v83
	ds_read_b128 v[80:83], v1 offset:16976
	s_waitcnt lgkmcnt(10)
	v_fmac_f32_e32 v65, v18, v112
	v_fmac_f32_e32 v66, v19, v113
	v_fmac_f32_e32 v67, v16, v114
	v_fmac_f32_e32 v68, v17, v115
	ds_read_b128 v[112:115], v1 offset:16992
	s_waitcnt lgkmcnt(10)
	v_fmac_f32_e32 v65, v14, v84
	v_fmac_f32_e32 v66, v15, v85
	v_fmac_f32_e32 v67, v12, v86
	v_fmac_f32_e32 v68, v13, v87
	ds_read_b128 v[84:87], v1 offset:17008
	s_waitcnt lgkmcnt(10)
	v_fmac_f32_e32 v65, v10, v96
	v_fmac_f32_e32 v66, v11, v97
	v_fmac_f32_e32 v67, v8, v98
	v_fmac_f32_e32 v68, v9, v99
	v_fmac_f32_e32 v65, v6, v92
	v_add_f32_e32 v65, v66, v65
	v_add_f32_e32 v66, v67, v68
	v_add_f32_e32 v65, v66, v65
	ds_read_b128 v[92:95], v1 offset:17024
	ds_read_b128 v[96:99], v1 offset:17040
	v_sub_f32_e32 v7, v7, v65
	s_waitcnt lgkmcnt(11)
	v_fma_f32 v65, v58, v116, 0
	v_fma_f32 v66, v0, v117, 0
	v_fma_f32 v67, v4, v118, 0
	v_fma_f32 v68, v5, v119, 0
	s_waitcnt lgkmcnt(10)
	v_fmac_f32_e32 v65, v59, v100
	v_fmac_f32_e32 v66, v60, v101
	v_fmac_f32_e32 v67, v61, v102
	v_fmac_f32_e32 v68, v62, v103
	ds_read_b128 v[100:103], v1 offset:17056
	s_waitcnt lgkmcnt(10)
; DI unsigned pack2(float a, float b) { hwf2 v = {a, b}; hwbf2 r = __builtin_convertvector(v, hwbf2); return __builtin_bit_cast(unsigned, r); }
; DI bf16_t f2bf(float x) { return (bf16_t)(pack2(x, 0.f) & 0xffffu); }
; DI int foff_perm(int r, int k) { const int kk = k & 15; return (((k >> 4) * 2 + ((kk >> 2) & 1)) * 32 + r) * 8 + (((kk >> 3) << 2) | (kk & 3)); }
; DI void phaseB1(const Params& p, int l, char* smem) {
;     ...
; #pragma unroll
;       for (int i = 1; i < 64; ++i) {
;         float s0 = 0.f, s1 = 0.f, s2 = 0.f, s3 = 0.f;
; #pragma unroll
;         for (int j4 = 0; j4 < i; j4 += 4) {
;           const float4 a = *(const float4*)(Am + i * 68 + j4);
;           s0 += a.x * x[j4];
;           if (j4 + 1 < i) s1 += a.y * x[j4 + 1];
;           if (j4 + 2 < i) s2 += a.z * x[j4 + 2];
;           if (j4 + 3 < i) s3 += a.w * x[j4 + 3];
;         }
;         x[i] = x[i] - ((s0 + s1) + (s2 + s3));
;       }
;       if (tid < 128) {
;         bf16_t* uT = p.b_uT + (size_t)u * 8192 + (tid >> 5) * 2048 + (tid & 31) * 4;
; #pragma unroll
;         for (int i4 = 0; i4 < 16; ++i4) {
;           uint2 o; o.x = pack2(x[4 * i4], x[4 * i4 + 1]); o.y = pack2(x[4 * i4 + 2], x[4 * i4 + 3]);
;           *(uint2*)(uT + i4 * 128) = o;
;         }
;       } else {
;         bf16_t* w = p.b_w + (size_t)u * 8192 + foff_perm(0, tid - 128);
; #pragma unroll
;         for (int i = 0; i < 64; ++i) w[(i >> 5) * 4096 + (i & 31) * 8] = f2bf(x[i]);
;       }
	v_fmac_f32_e32 v65, v63, v104
	v_fmac_f32_e32 v66, v64, v105
	v_fmac_f32_e32 v67, v56, v106
	v_fmac_f32_e32 v68, v57, v107
	ds_read_b128 v[104:107], v1 offset:17072
	s_waitcnt lgkmcnt(10)
	v_fmac_f32_e32 v65, v54, v76
	v_fmac_f32_e32 v66, v55, v77
	v_fmac_f32_e32 v67, v52, v78
	v_fmac_f32_e32 v68, v53, v79
	ds_read_b128 v[76:79], v1 offset:17088
	s_waitcnt lgkmcnt(10)
	v_fmac_f32_e32 v65, v50, v88
	v_fmac_f32_e32 v66, v51, v89
	v_fmac_f32_e32 v67, v48, v90
	v_fmac_f32_e32 v68, v49, v91
	ds_read_b64 v[88:89], v1 offset:17104
	s_waitcnt lgkmcnt(10)
	v_fmac_f32_e32 v65, v46, v108
	v_fmac_f32_e32 v66, v47, v109
	v_fmac_f32_e32 v67, v44, v110
	v_fmac_f32_e32 v68, v45, v111
	ds_read_b128 v[108:111], v1 offset:17136
	s_waitcnt lgkmcnt(10)
	v_fmac_f32_e32 v65, v42, v120
	v_fmac_f32_e32 v66, v43, v121
	v_fmac_f32_e32 v67, v40, v122
	v_fmac_f32_e32 v68, v41, v123
	ds_read_b128 v[116:119], v1 offset:17152
	s_waitcnt lgkmcnt(10)
	v_fmac_f32_e32 v65, v38, v80
	v_fmac_f32_e32 v66, v39, v81
	v_fmac_f32_e32 v67, v36, v82
	v_fmac_f32_e32 v68, v37, v83
	ds_read_b128 v[80:83], v1 offset:17168
	s_waitcnt lgkmcnt(10)
	v_fmac_f32_e32 v65, v34, v112
	v_fmac_f32_e32 v66, v35, v113
	v_fmac_f32_e32 v67, v32, v114
	v_fmac_f32_e32 v68, v33, v115
	ds_read_b128 v[112:115], v1 offset:17184
	s_waitcnt lgkmcnt(10)
	v_fmac_f32_e32 v65, v30, v84
	v_fmac_f32_e32 v66, v31, v85
	v_fmac_f32_e32 v67, v28, v86
	v_fmac_f32_e32 v68, v29, v87
	ds_read_b128 v[84:87], v1 offset:17200
	s_waitcnt lgkmcnt(10)
	v_fmac_f32_e32 v65, v26, v92
	v_fmac_f32_e32 v66, v27, v93
	v_fmac_f32_e32 v67, v24, v94
	v_fmac_f32_e32 v68, v25, v95
	ds_read_b128 v[92:95], v1 offset:17216
	s_waitcnt lgkmcnt(10)
	v_fmac_f32_e32 v65, v22, v96
	v_fmac_f32_e32 v66, v23, v97
	v_fmac_f32_e32 v67, v20, v98
	v_fmac_f32_e32 v68, v21, v99
	ds_read_b128 v[96:99], v1 offset:17232
	s_waitcnt lgkmcnt(10)
	v_fmac_f32_e32 v65, v18, v100
	v_fmac_f32_e32 v66, v19, v101
	v_fmac_f32_e32 v67, v16, v102
	v_fmac_f32_e32 v68, v17, v103
	ds_read_b128 v[100:103], v1 offset:17248
	s_waitcnt lgkmcnt(10)
	v_fmac_f32_e32 v65, v14, v104
	v_fmac_f32_e32 v66, v15, v105
	v_fmac_f32_e32 v67, v12, v106
	v_fmac_f32_e32 v68, v13, v107
	ds_read_b128 v[104:107], v1 offset:17264
	s_waitcnt lgkmcnt(10)
	v_fmac_f32_e32 v65, v10, v76
	v_fmac_f32_e32 v66, v11, v77
	ds_read_b128 v[120:123], v1 offset:17280
	v_fmac_f32_e32 v67, v8, v78
	v_fmac_f32_e32 v68, v9, v79
	s_waitcnt lgkmcnt(10)
	v_fmac_f32_e32 v65, v6, v88
	v_fmac_f32_e32 v66, v7, v89
	v_add_f32_e32 v65, v65, v66
	v_add_f32_e32 v66, v67, v68
	v_add_f32_e32 v65, v66, v65
	ds_read_b128 v[76:79], v1 offset:17296
	ds_read_b128 v[88:91], v1 offset:17312
	v_sub_f32_e32 v2, v2, v65
	s_waitcnt lgkmcnt(11)
	v_fma_f32 v65, v58, v108, 0
	v_fma_f32 v66, v0, v109, 0
	v_fma_f32 v67, v4, v110, 0
	v_fma_f32 v68, v5, v111, 0
	s_waitcnt lgkmcnt(10)
	v_fmac_f32_e32 v65, v59, v116
	v_fmac_f32_e32 v66, v60, v117
	v_fmac_f32_e32 v67, v61, v118
	v_fmac_f32_e32 v68, v62, v119
	ds_read_b128 v[108:111], v1 offset:17328
	s_waitcnt lgkmcnt(10)
	v_fmac_f32_e32 v65, v63, v80
	v_fmac_f32_e32 v66, v64, v81
	v_fmac_f32_e32 v67, v56, v82
	v_fmac_f32_e32 v68, v57, v83
	ds_read_b128 v[80:83], v1 offset:17344
	s_waitcnt lgkmcnt(10)
	v_fmac_f32_e32 v65, v54, v112
	v_fmac_f32_e32 v66, v55, v113
	v_fmac_f32_e32 v67, v52, v114
	v_fmac_f32_e32 v68, v53, v115
	ds_read_b128 v[112:115], v1 offset:17360
	s_waitcnt lgkmcnt(10)
	v_fmac_f32_e32 v65, v50, v84
	v_fmac_f32_e32 v66, v51, v85
	v_fmac_f32_e32 v67, v48, v86
	v_fmac_f32_e32 v68, v49, v87
	ds_read_b96 v[84:86], v1 offset:17376
	s_waitcnt lgkmcnt(10)
	v_fmac_f32_e32 v65, v46, v92
	v_fmac_f32_e32 v66, v47, v93
	v_fmac_f32_e32 v67, v44, v94
	v_fmac_f32_e32 v68, v45, v95
	s_waitcnt lgkmcnt(9)
	v_fmac_f32_e32 v65, v42, v96
	v_fmac_f32_e32 v66, v43, v97
	v_fmac_f32_e32 v67, v40, v98
	v_fmac_f32_e32 v68, v41, v99
	s_waitcnt lgkmcnt(8)
	v_fmac_f32_e32 v65, v38, v100
	v_fmac_f32_e32 v66, v39, v101
	v_fmac_f32_e32 v67, v36, v102
	v_fmac_f32_e32 v68, v37, v103
	s_waitcnt lgkmcnt(7)
	v_fmac_f32_e32 v65, v34, v104
	v_fmac_f32_e32 v66, v35, v105
	v_fmac_f32_e32 v67, v32, v106
	v_fmac_f32_e32 v68, v33, v107
	s_waitcnt lgkmcnt(6)
	v_fmac_f32_e32 v65, v30, v120
	v_fmac_f32_e32 v66, v31, v121
	v_fmac_f32_e32 v67, v28, v122
	v_fmac_f32_e32 v68, v29, v123
	s_waitcnt lgkmcnt(5)
	v_fmac_f32_e32 v65, v26, v76
	v_fmac_f32_e32 v66, v27, v77
	v_fmac_f32_e32 v67, v24, v78
	v_fmac_f32_e32 v68, v25, v79
	s_waitcnt lgkmcnt(4)
	v_fmac_f32_e32 v65, v22, v88
	v_fmac_f32_e32 v66, v23, v89
	v_fmac_f32_e32 v67, v20, v90
	v_fmac_f32_e32 v68, v21, v91
	s_waitcnt lgkmcnt(3)
	v_fmac_f32_e32 v65, v18, v108
	v_fmac_f32_e32 v66, v19, v109
	v_fmac_f32_e32 v67, v16, v110
	v_fmac_f32_e32 v68, v17, v111
	s_waitcnt lgkmcnt(2)
	v_fmac_f32_e32 v65, v14, v80
	v_fmac_f32_e32 v66, v15, v81
	v_fmac_f32_e32 v67, v12, v82
	v_fmac_f32_e32 v68, v13, v83
	s_waitcnt lgkmcnt(1)
	v_fmac_f32_e32 v65, v10, v112
	v_fmac_f32_e32 v66, v11, v113
	v_fmac_f32_e32 v67, v8, v114
	v_fmac_f32_e32 v68, v9, v115
	s_waitcnt lgkmcnt(0)
	v_fmac_f32_e32 v65, v6, v84
	v_fmac_f32_e32 v66, v7, v85
	v_fmac_f32_e32 v67, v2, v86
	v_add_f32_e32 v65, v65, v66
	v_add_f32_e32 v66, v68, v67
	v_add_f32_e32 v65, v66, v65
	v_sub_f32_e32 v3, v3, v65
	s_and_saveexec_b64 s[2:3], s[4:5]
	s_xor_b64 s[70:71], exec, s[2:3]
	s_cbranch_execz .LBB0_1951
; DI bf16_t f2bf(float x) { return (bf16_t)(pack2(x, 0.f) & 0xffffu); }
; DI int foff_perm(int r, int k) { const int kk = k & 15; return (((k >> 4) * 2 + ((kk >> 2) & 1)) * 32 + r) * 8 + (((kk >> 3) << 2) | (kk & 3)); }
; DI void phaseB1(const Params& p, int l, char* smem) {
;     ...
;       } else {
;         bf16_t* w = p.b_w + (size_t)u * 8192 + foff_perm(0, tid - 128);
; #pragma unroll
;         for (int i = 0; i < 64; ++i) w[(i >> 5) * 4096 + (i & 31) * 8] = f2bf(x[i]);
;       }
	v_lshl_add_u64 v[66:67], s[68:69], 1, v[166:167]
	v_cvt_pk_bf16_f32 v0, v0, s0
	global_store_short v[66:67], v0, off offset:16
	v_cvt_pk_bf16_f32 v0, v4, s0
	global_store_short v[66:67], v0, off offset:32
	v_cvt_pk_bf16_f32 v0, v5, s0
	global_store_short v[66:67], v0, off offset:48
	v_cvt_pk_bf16_f32 v0, v59, s0
	global_store_short v[66:67], v0, off offset:64
	v_cvt_pk_bf16_f32 v0, v60, s0
	global_store_short v[66:67], v0, off offset:80
	v_cvt_pk_bf16_f32 v0, v61, s0
	global_store_short v[66:67], v0, off offset:96
	v_cvt_pk_bf16_f32 v0, v62, s0
	global_store_short v[66:67], v0, off offset:112
	v_cvt_pk_bf16_f32 v0, v63, s0
	global_store_short v[66:67], v0, off offset:128
	v_cvt_pk_bf16_f32 v0, v64, s0
	global_store_short v[66:67], v0, off offset:144
	v_cvt_pk_bf16_f32 v0, v56, s0
	global_store_short v[66:67], v0, off offset:160
	v_cvt_pk_bf16_f32 v0, v57, s0
	global_store_short v[66:67], v0, off offset:176
	v_cvt_pk_bf16_f32 v0, v54, s0
	global_store_short v[66:67], v0, off offset:192
	v_cvt_pk_bf16_f32 v0, v55, s0
	global_store_short v[66:67], v0, off offset:208
	v_cvt_pk_bf16_f32 v0, v52, s0
	global_store_short v[66:67], v0, off offset:224
	v_cvt_pk_bf16_f32 v0, v53, s0
	global_store_short v[66:67], v0, off offset:240
	v_cvt_pk_bf16_f32 v0, v50, s0
	global_store_short v[66:67], v0, off offset:256
	v_cvt_pk_bf16_f32 v0, v51, s0
	global_store_short v[66:67], v0, off offset:272
	v_cvt_pk_bf16_f32 v0, v48, s0
	global_store_short v[66:67], v0, off offset:288
	v_cvt_pk_bf16_f32 v0, v49, s0
	global_store_short v[66:67], v0, off offset:304
	v_cvt_pk_bf16_f32 v0, v46, s0
	global_store_short v[66:67], v0, off offset:320
	v_cvt_pk_bf16_f32 v0, v47, s0
	global_store_short v[66:67], v0, off offset:336
	v_cvt_pk_bf16_f32 v0, v44, s0
	global_store_short v[66:67], v0, off offset:352
	v_cvt_pk_bf16_f32 v0, v45, s0
	global_store_short v[66:67], v0, off offset:368
	v_cvt_pk_bf16_f32 v0, v42, s0
	global_store_short v[66:67], v0, off offset:384
	v_cvt_pk_bf16_f32 v0, v43, s0
	global_store_short v[66:67], v0, off offset:400
	v_cvt_pk_bf16_f32 v0, v40, s0
	global_store_short v[66:67], v0, off offset:416
	v_cvt_pk_bf16_f32 v0, v41, s0
	global_store_short v[66:67], v0, off offset:432
	v_cvt_pk_bf16_f32 v0, v38, s0
	global_store_short v[66:67], v0, off offset:448
	v_cvt_pk_bf16_f32 v0, v39, s0
	global_store_short v[66:67], v0, off offset:464
	v_cvt_pk_bf16_f32 v0, v36, s0
	global_store_short v[66:67], v0, off offset:480
	v_cvt_pk_bf16_f32 v0, v37, s0
	v_add_co_u32_e32 v4, vcc, s80, v66
	global_store_short v[66:67], v0, off offset:496
	v_cvt_pk_bf16_f32 v0, v34, s0
	v_addc_co_u32_e32 v5, vcc, 0, v67, vcc
	global_store_short v[4:5], v0, off
	v_cvt_pk_bf16_f32 v0, v35, s0
	global_store_short v[4:5], v0, off offset:16
	v_cvt_pk_bf16_f32 v0, v32, s0
	global_store_short v[4:5], v0, off offset:32
	v_cvt_pk_bf16_f32 v0, v33, s0
	global_store_short v[4:5], v0, off offset:48
	v_cvt_pk_bf16_f32 v0, v30, s0
	global_store_short v[4:5], v0, off offset:64
	v_cvt_pk_bf16_f32 v0, v31, s0
	global_store_short v[4:5], v0, off offset:80
	v_cvt_pk_bf16_f32 v0, v28, s0
	global_store_short v[4:5], v0, off offset:96
	v_cvt_pk_bf16_f32 v0, v29, s0
	global_store_short v[4:5], v0, off offset:112
	v_cvt_pk_bf16_f32 v0, v26, s0
	global_store_short v[4:5], v0, off offset:128
	v_cvt_pk_bf16_f32 v0, v27, s0
	global_store_short v[4:5], v0, off offset:144
	v_cvt_pk_bf16_f32 v0, v24, s0
	global_store_short v[4:5], v0, off offset:160
	v_cvt_pk_bf16_f32 v0, v25, s0
	global_store_short v[4:5], v0, off offset:176
	v_cvt_pk_bf16_f32 v0, v22, s0
	global_store_short v[4:5], v0, off offset:192
	v_cvt_pk_bf16_f32 v0, v23, s0
	global_store_short v[4:5], v0, off offset:208
	v_cvt_pk_bf16_f32 v0, v20, s0
	global_store_short v[4:5], v0, off offset:224
	v_cvt_pk_bf16_f32 v0, v21, s0
	global_store_short v[4:5], v0, off offset:240
	v_cvt_pk_bf16_f32 v0, v18, s0
	global_store_short v[4:5], v0, off offset:256
	v_cvt_pk_bf16_f32 v0, v19, s0
	global_store_short v[4:5], v0, off offset:272
	v_cvt_pk_bf16_f32 v0, v16, s0
	global_store_short v[4:5], v0, off offset:288
	v_cvt_pk_bf16_f32 v0, v17, s0
	global_store_short v[4:5], v0, off offset:304
	v_cvt_pk_bf16_f32 v0, v14, s0
	global_store_short v[4:5], v0, off offset:320
	v_cvt_pk_bf16_f32 v0, v15, s0
	global_store_short v[4:5], v0, off offset:336
	v_cvt_pk_bf16_f32 v0, v12, s0
	global_store_short v[4:5], v0, off offset:352
	v_cvt_pk_bf16_f32 v0, v13, s0
	global_store_short v[4:5], v0, off offset:368
	v_cvt_pk_bf16_f32 v0, v10, s0
	global_store_short v[4:5], v0, off offset:384
	v_cvt_pk_bf16_f32 v0, v11, s0
	global_store_short v[4:5], v0, off offset:400
	v_cvt_pk_bf16_f32 v0, v8, s0
	global_store_short v[4:5], v0, off offset:416
	v_cvt_pk_bf16_f32 v0, v9, s0
	global_store_short v[4:5], v0, off offset:432
	v_cvt_pk_bf16_f32 v0, v6, s0
	global_store_short v[4:5], v0, off offset:448
	v_cvt_pk_bf16_f32 v0, v7, s0
	v_cvt_pk_bf16_f32 v58, v58, s0
	global_store_short v[4:5], v0, off offset:464
	v_cvt_pk_bf16_f32 v0, v2, s0
	global_store_short v[66:67], v58, off
	global_store_short v[4:5], v0, off offset:480
	v_cvt_pk_bf16_f32 v0, v3, s0
	global_store_short v[4:5], v0, off offset:496
